# passC pooling: every conditional U-row load of a half-chunk now in flight together (writes to LDS deferred behind one wait, after the masked last row group)
# speedup vs baseline: 1.0084x; 1.0022x over previous
.LBB0_485:
	s_or_b64 exec, exec, s[0:1]
	s_waitcnt vmcnt(0)
	v_add_u32_e32 v18, v10, v11
	ds_write_b128 v18, v[226:229]
	v_add_u32_e32 v19, v10, v12
	ds_write_b128 v19, v[230:233]
	v_add_u32_e32 v20, v10, v13
	ds_write_b128 v20, v[234:237]
	v_add_u32_e32 v4, v10, v14
	ds_write_b128 v4, v[238:241]
	s_sub_i32 s0, s24, s26
	s_or_b32 s4, s0, 1
	s_max_i32 s1, s0, 1
	s_min_i32 s5, s4, s25
	s_sub_i32 s1, s5, s1
	s_waitcnt lgkmcnt(0)
	s_add_i32 s1, s1, 1
	ds_read_u16 v0, v16
	ds_read_u16 v2, v16 offset:128
	v_cvt_f32_i32_e32 v3, s1
	s_max_i32 s1, s4, 1
	s_or_b32 s4, s0, 2
	s_waitcnt lgkmcnt(1)
	v_lshlrev_b32_e32 v0, 16, v0
	v_rcp_iflag_f32_e32 v3, v3
	v_add_f32_e32 v1, 0, v0
	s_waitcnt lgkmcnt(0)
	v_lshlrev_b32_e32 v2, 16, v2
	v_add_f32_e32 v1, v1, v2
	v_fma_f32 v3, v3, v1, -v2
	s_min_i32 s5, s4, s25
	v_bfe_u32 v5, v3, 16, 1
	s_sub_i32 s1, s5, s1
	v_add3_u32 v3, v3, v5, s67
	s_add_i32 s1, s1, 1
	ds_write_b16_d16_hi v16, v3 offset:8192
	v_cvt_f32_i32_e32 v3, s1
	v_sub_f32_e32 v0, v1, v0
	ds_read_u16 v1, v16 offset:256
	s_max_i32 s1, s4, 1
	v_rcp_iflag_f32_e32 v3, v3
	s_or_b32 s4, s0, 3
	s_min_i32 s5, s4, s25
	s_waitcnt lgkmcnt(0)
	v_lshlrev_b32_e32 v1, 16, v1
	v_add_f32_e32 v0, v0, v1
	v_fma_f32 v3, v3, v0, -v1
	v_bfe_u32 v5, v3, 16, 1
	s_sub_i32 s1, s5, s1
	v_add3_u32 v3, v3, v5, s67
	s_add_i32 s1, s1, 1
	ds_write_b16_d16_hi v16, v3 offset:8320
	v_cvt_f32_i32_e32 v3, s1
	v_sub_f32_e32 v0, v0, v2
	ds_read_u16 v2, v16 offset:384
	s_max_i32 s1, s4, 1
	v_rcp_iflag_f32_e32 v3, v3
	s_or_b32 s4, s0, 4
	s_min_i32 s5, s4, s25
	s_waitcnt lgkmcnt(0)
	v_lshlrev_b32_e32 v2, 16, v2
	v_add_f32_e32 v0, v0, v2
	v_fma_f32 v3, v3, v0, -v2
	v_bfe_u32 v5, v3, 16, 1
	s_sub_i32 s1, s5, s1
	v_add3_u32 v3, v3, v5, s67
	s_add_i32 s1, s1, 1
	ds_write_b16_d16_hi v16, v3 offset:8448
	v_cvt_f32_i32_e32 v3, s1
	v_sub_f32_e32 v0, v0, v1
	ds_read_u16 v1, v16 offset:512
	s_max_i32 s1, s4, 1
	v_rcp_iflag_f32_e32 v3, v3
	s_or_b32 s4, s0, 5
	s_min_i32 s5, s4, s25
	s_waitcnt lgkmcnt(0)
	v_lshlrev_b32_e32 v1, 16, v1
	v_add_f32_e32 v0, v0, v1
	v_fma_f32 v3, v3, v0, -v1
	v_bfe_u32 v5, v3, 16, 1
	s_sub_i32 s1, s5, s1
	v_add3_u32 v3, v3, v5, s67
	s_add_i32 s1, s1, 1
	ds_write_b16_d16_hi v16, v3 offset:8576
	v_cvt_f32_i32_e32 v3, s1
	v_sub_f32_e32 v0, v0, v2
	ds_read_u16 v2, v16 offset:640
	s_or_b32 s1, s0, 6
	v_rcp_iflag_f32_e32 v3, v3
	s_max_i32 s4, s4, 1
	s_min_i32 s5, s1, s25
	s_waitcnt lgkmcnt(0)
	v_lshlrev_b32_e32 v2, 16, v2
	v_add_f32_e32 v0, v0, v2
	v_fma_f32 v3, v3, v0, -v2
	v_bfe_u32 v5, v3, 16, 1
	s_sub_i32 s4, s5, s4
	v_add3_u32 v3, v3, v5, s67
	s_add_i32 s4, s4, 1
	ds_write_b16_d16_hi v16, v3 offset:8704
	v_cvt_f32_i32_e32 v3, s4
	v_sub_f32_e32 v0, v0, v1
	ds_read_u16 v1, v16 offset:768
	s_or_b32 s4, s0, 7
	v_rcp_iflag_f32_e32 v3, v3
	s_max_i32 s1, s1, 1
	s_min_i32 s5, s4, s25
	s_waitcnt lgkmcnt(0)
	v_lshlrev_b32_e32 v1, 16, v1
	v_add_f32_e32 v0, v0, v1
	v_fma_f32 v3, v3, v0, -v1
	v_bfe_u32 v5, v3, 16, 1
	s_sub_i32 s1, s5, s1
	v_add3_u32 v3, v3, v5, s67
	s_add_i32 s1, s1, 1
	ds_write_b16_d16_hi v16, v3 offset:8832
	v_cvt_f32_i32_e32 v3, s1
	v_sub_f32_e32 v0, v0, v2
	ds_read_u16 v2, v16 offset:896
	s_max_i32 s1, s4, 1
	v_rcp_iflag_f32_e32 v3, v3
	s_or_b32 s4, s0, 8
	s_min_i32 s5, s4, s25
	s_waitcnt lgkmcnt(0)
	v_lshlrev_b32_e32 v2, 16, v2
	v_add_f32_e32 v0, v0, v2
	v_fma_f32 v3, v3, v0, -v2
	v_bfe_u32 v5, v3, 16, 1
	s_sub_i32 s1, s5, s1
	v_add3_u32 v3, v3, v5, s67
	s_add_i32 s1, s1, 1
	ds_write_b16_d16_hi v16, v3 offset:8960
	v_cvt_f32_i32_e32 v3, s1
	v_sub_f32_e32 v0, v0, v1
	ds_read_u16 v1, v16 offset:1024
	s_max_i32 s1, s4, 1
	v_rcp_iflag_f32_e32 v3, v3
	s_or_b32 s4, s0, 9
	s_min_i32 s5, s4, s25
	s_waitcnt lgkmcnt(0)
	v_lshlrev_b32_e32 v1, 16, v1
	v_add_f32_e32 v0, v0, v1
	v_fma_f32 v3, v3, v0, -v1
	v_bfe_u32 v5, v3, 16, 1
	s_sub_i32 s1, s5, s1
	v_add3_u32 v3, v3, v5, s67
	s_add_i32 s1, s1, 1
	ds_write_b16_d16_hi v16, v3 offset:9088
	v_cvt_f32_i32_e32 v3, s1
	v_sub_f32_e32 v0, v0, v2
	ds_read_u16 v2, v16 offset:1152
	s_max_i32 s1, s4, 1
	v_rcp_iflag_f32_e32 v3, v3
	s_or_b32 s4, s0, 10
	s_min_i32 s5, s4, s25
	s_waitcnt lgkmcnt(0)
	v_lshlrev_b32_e32 v2, 16, v2
	v_add_f32_e32 v0, v0, v2
	v_fma_f32 v3, v3, v0, -v2
	v_bfe_u32 v5, v3, 16, 1
	s_sub_i32 s1, s5, s1
	v_add3_u32 v3, v3, v5, s67
	s_add_i32 s1, s1, 1
	ds_write_b16_d16_hi v16, v3 offset:9216
	v_cvt_f32_i32_e32 v3, s1
	v_sub_f32_e32 v0, v0, v1
	ds_read_u16 v1, v16 offset:1280
	s_max_i32 s1, s4, 1
	v_rcp_iflag_f32_e32 v3, v3
	s_or_b32 s4, s0, 11
	s_min_i32 s5, s4, s25
	s_waitcnt lgkmcnt(0)
	v_lshlrev_b32_e32 v1, 16, v1
	v_add_f32_e32 v0, v0, v1
	v_fma_f32 v3, v3, v0, -v1
	v_bfe_u32 v5, v3, 16, 1
	s_sub_i32 s1, s5, s1
	v_add3_u32 v3, v3, v5, s67
	s_add_i32 s1, s1, 1
	ds_write_b16_d16_hi v16, v3 offset:9344
	v_cvt_f32_i32_e32 v3, s1
	v_sub_f32_e32 v0, v0, v2
	ds_read_u16 v2, v16 offset:1408
	s_max_i32 s1, s4, 1
	v_rcp_iflag_f32_e32 v3, v3
	s_or_b32 s4, s0, 12
	s_min_i32 s5, s4, s25
	s_waitcnt lgkmcnt(0)
	v_lshlrev_b32_e32 v2, 16, v2
	v_add_f32_e32 v0, v0, v2
	v_fma_f32 v3, v3, v0, -v2
	v_bfe_u32 v5, v3, 16, 1
	s_sub_i32 s1, s5, s1
	v_add3_u32 v3, v3, v5, s67
	s_add_i32 s1, s1, 1
	ds_write_b16_d16_hi v16, v3 offset:9472
	v_cvt_f32_i32_e32 v3, s1
	v_sub_f32_e32 v0, v0, v1
	ds_read_u16 v1, v16 offset:1536
	s_max_i32 s1, s4, 1
	v_rcp_iflag_f32_e32 v3, v3
	s_or_b32 s4, s0, 13
	s_min_i32 s5, s4, s25
	s_waitcnt lgkmcnt(0)
	v_lshlrev_b32_e32 v1, 16, v1
	v_add_f32_e32 v0, v0, v1
	v_fma_f32 v3, v3, v0, -v1
	v_bfe_u32 v5, v3, 16, 1
	s_sub_i32 s1, s5, s1
	v_add3_u32 v3, v3, v5, s67
	s_add_i32 s1, s1, 1
	ds_write_b16_d16_hi v16, v3 offset:9600
	v_cvt_f32_i32_e32 v3, s1
	v_sub_f32_e32 v0, v0, v2
	ds_read_u16 v2, v16 offset:1664
	s_or_b32 s1, s0, 14
	v_rcp_iflag_f32_e32 v3, v3
	s_max_i32 s4, s4, 1
	s_min_i32 s5, s1, s25
	s_waitcnt lgkmcnt(0)
	v_lshlrev_b32_e32 v2, 16, v2
	v_add_f32_e32 v0, v0, v2
	v_fma_f32 v3, v3, v0, -v2
	v_bfe_u32 v5, v3, 16, 1
	s_sub_i32 s4, s5, s4
	v_add3_u32 v3, v3, v5, s67
	s_add_i32 s4, s4, 1
	ds_write_b16_d16_hi v16, v3 offset:9728
	v_cvt_f32_i32_e32 v3, s4
	v_sub_f32_e32 v0, v0, v1
	ds_read_u16 v1, v16 offset:1792
	s_or_b32 s4, s0, 15
	v_rcp_iflag_f32_e32 v3, v3
	s_max_i32 s1, s1, 1
	s_min_i32 s5, s4, s25
	s_waitcnt lgkmcnt(0)
	v_lshlrev_b32_e32 v1, 16, v1
	v_add_f32_e32 v0, v0, v1
	v_fma_f32 v3, v3, v0, -v1
	v_bfe_u32 v5, v3, 16, 1
	s_sub_i32 s1, s5, s1
	v_add3_u32 v3, v3, v5, s67
	s_add_i32 s1, s1, 1
	ds_write_b16_d16_hi v16, v3 offset:9856
	v_cvt_f32_i32_e32 v3, s1
	v_sub_f32_e32 v0, v0, v2
	ds_read_u16 v2, v16 offset:1920
	s_max_i32 s1, s4, 1
	v_rcp_iflag_f32_e32 v3, v3
	s_or_b32 s4, s0, 16
	s_min_i32 s5, s4, s25
	s_waitcnt lgkmcnt(0)
	v_lshlrev_b32_e32 v2, 16, v2
	v_add_f32_e32 v0, v0, v2
	v_fma_f32 v3, v3, v0, -v2
	v_bfe_u32 v5, v3, 16, 1
	s_sub_i32 s1, s5, s1
	v_add3_u32 v3, v3, v5, s67
	s_add_i32 s1, s1, 1
	ds_write_b16_d16_hi v16, v3 offset:9984
	v_cvt_f32_i32_e32 v3, s1
	v_sub_f32_e32 v0, v0, v1
	ds_read_u16 v1, v16 offset:2048
	s_max_i32 s1, s4, 1
	v_rcp_iflag_f32_e32 v3, v3
	s_or_b32 s4, s0, 17
	s_min_i32 s5, s4, s25
	s_waitcnt lgkmcnt(0)
	v_lshlrev_b32_e32 v1, 16, v1
	v_add_f32_e32 v0, v0, v1
	v_fma_f32 v3, v3, v0, -v1
	v_bfe_u32 v5, v3, 16, 1
	s_sub_i32 s1, s5, s1
	v_add3_u32 v3, v3, v5, s67
	s_add_i32 s1, s1, 1
	ds_write_b16_d16_hi v16, v3 offset:10112
	v_cvt_f32_i32_e32 v3, s1
	v_sub_f32_e32 v0, v0, v2
	ds_read_u16 v2, v16 offset:2176
	s_max_i32 s1, s4, 1
	v_rcp_iflag_f32_e32 v3, v3
	s_or_b32 s4, s0, 18
	s_min_i32 s5, s4, s25
	s_waitcnt lgkmcnt(0)
	v_lshlrev_b32_e32 v2, 16, v2
	v_add_f32_e32 v0, v0, v2
	v_fma_f32 v3, v3, v0, -v2
	v_bfe_u32 v5, v3, 16, 1
	s_sub_i32 s1, s5, s1
	v_add3_u32 v3, v3, v5, s67
	s_add_i32 s1, s1, 1
	ds_write_b16_d16_hi v16, v3 offset:10240
	v_cvt_f32_i32_e32 v3, s1
	v_sub_f32_e32 v0, v0, v1
	ds_read_u16 v1, v16 offset:2304
	s_max_i32 s1, s4, 1
	v_rcp_iflag_f32_e32 v3, v3
	s_or_b32 s4, s0, 19
	s_min_i32 s5, s4, s25
	s_waitcnt lgkmcnt(0)
	v_lshlrev_b32_e32 v1, 16, v1
	v_add_f32_e32 v0, v0, v1
	v_fma_f32 v3, v3, v0, -v1
	v_bfe_u32 v5, v3, 16, 1
	s_sub_i32 s1, s5, s1
	v_add3_u32 v3, v3, v5, s67
	s_add_i32 s1, s1, 1
	ds_write_b16_d16_hi v16, v3 offset:10368
	v_cvt_f32_i32_e32 v3, s1
	v_sub_f32_e32 v0, v0, v2
	ds_read_u16 v2, v16 offset:2432
	s_max_i32 s1, s4, 1
	v_rcp_iflag_f32_e32 v3, v3
	s_or_b32 s4, s0, 20
	s_min_i32 s5, s4, s25
	s_waitcnt lgkmcnt(0)
	v_lshlrev_b32_e32 v2, 16, v2
	v_add_f32_e32 v0, v0, v2
	v_fma_f32 v3, v3, v0, -v2
	v_bfe_u32 v5, v3, 16, 1
	s_sub_i32 s1, s5, s1
	v_add3_u32 v3, v3, v5, s67
	s_add_i32 s1, s1, 1
	ds_write_b16_d16_hi v16, v3 offset:10496
	v_cvt_f32_i32_e32 v3, s1
	v_sub_f32_e32 v0, v0, v1
	ds_read_u16 v1, v16 offset:2560
	s_max_i32 s1, s4, 1
	v_rcp_iflag_f32_e32 v3, v3
	s_or_b32 s4, s0, 21
	s_min_i32 s5, s4, s25
	s_waitcnt lgkmcnt(0)
	v_lshlrev_b32_e32 v1, 16, v1
	v_add_f32_e32 v0, v0, v1
	v_fma_f32 v3, v3, v0, -v1
	v_bfe_u32 v5, v3, 16, 1
	s_sub_i32 s1, s5, s1
	v_add3_u32 v3, v3, v5, s67
	s_add_i32 s1, s1, 1
	ds_write_b16_d16_hi v16, v3 offset:10624
	v_cvt_f32_i32_e32 v3, s1
	v_sub_f32_e32 v0, v0, v2
	ds_read_u16 v2, v16 offset:2688
	s_or_b32 s1, s0, 22
	v_rcp_iflag_f32_e32 v3, v3
	s_max_i32 s4, s4, 1
	s_min_i32 s5, s1, s25
	s_waitcnt lgkmcnt(0)
	v_lshlrev_b32_e32 v2, 16, v2
	v_add_f32_e32 v0, v0, v2
	v_fma_f32 v3, v3, v0, -v2
	v_bfe_u32 v5, v3, 16, 1
	s_sub_i32 s4, s5, s4
	v_add3_u32 v3, v3, v5, s67
	s_add_i32 s4, s4, 1
	ds_write_b16_d16_hi v16, v3 offset:10752
	v_cvt_f32_i32_e32 v3, s4
	v_sub_f32_e32 v0, v0, v1
	ds_read_u16 v1, v16 offset:2816
	s_or_b32 s4, s0, 23
	v_rcp_iflag_f32_e32 v3, v3
	s_max_i32 s1, s1, 1
	s_min_i32 s5, s4, s25
	s_waitcnt lgkmcnt(0)
	v_lshlrev_b32_e32 v1, 16, v1
	v_add_f32_e32 v0, v0, v1
	v_fma_f32 v3, v3, v0, -v1
	v_bfe_u32 v5, v3, 16, 1
	s_sub_i32 s1, s5, s1
	v_add3_u32 v3, v3, v5, s67
	s_add_i32 s1, s1, 1
	ds_write_b16_d16_hi v16, v3 offset:10880
	v_cvt_f32_i32_e32 v3, s1
	v_sub_f32_e32 v0, v0, v2
	ds_read_u16 v2, v16 offset:2944
	s_max_i32 s1, s4, 1
	v_rcp_iflag_f32_e32 v3, v3
	s_or_b32 s4, s0, 24
	s_min_i32 s5, s4, s25
	s_waitcnt lgkmcnt(0)
	v_lshlrev_b32_e32 v2, 16, v2
	v_add_f32_e32 v0, v0, v2
	v_fma_f32 v3, v3, v0, -v2
	v_bfe_u32 v5, v3, 16, 1
	s_sub_i32 s1, s5, s1
	v_add3_u32 v3, v3, v5, s67
	s_add_i32 s1, s1, 1
	ds_write_b16_d16_hi v16, v3 offset:11008
	v_cvt_f32_i32_e32 v3, s1
	v_sub_f32_e32 v0, v0, v1
	ds_read_u16 v1, v16 offset:3072
	s_max_i32 s1, s4, 1
	v_rcp_iflag_f32_e32 v3, v3
	s_or_b32 s4, s0, 25
	s_min_i32 s5, s4, s25
	s_waitcnt lgkmcnt(0)
	v_lshlrev_b32_e32 v1, 16, v1
	v_add_f32_e32 v0, v0, v1
	v_fma_f32 v3, v3, v0, -v1
	v_bfe_u32 v5, v3, 16, 1
	s_sub_i32 s1, s5, s1
	v_add3_u32 v3, v3, v5, s67
	s_add_i32 s1, s1, 1
	ds_write_b16_d16_hi v16, v3 offset:11136
	v_cvt_f32_i32_e32 v3, s1
	v_sub_f32_e32 v0, v0, v2
	ds_read_u16 v2, v16 offset:3200
	s_max_i32 s1, s4, 1
	v_rcp_iflag_f32_e32 v3, v3
	s_or_b32 s4, s0, 26
	s_min_i32 s5, s4, s25
	s_waitcnt lgkmcnt(0)
	v_lshlrev_b32_e32 v2, 16, v2
	v_add_f32_e32 v0, v0, v2
	v_fma_f32 v3, v3, v0, -v2
	v_bfe_u32 v5, v3, 16, 1
	s_sub_i32 s1, s5, s1
	v_add3_u32 v3, v3, v5, s67
	s_add_i32 s1, s1, 1
	ds_write_b16_d16_hi v16, v3 offset:11264
	v_cvt_f32_i32_e32 v3, s1
	v_sub_f32_e32 v0, v0, v1
	ds_read_u16 v1, v16 offset:3328
	s_max_i32 s1, s4, 1
	v_rcp_iflag_f32_e32 v3, v3
	s_or_b32 s4, s0, 27
	s_min_i32 s5, s4, s25
	s_waitcnt lgkmcnt(0)
	v_lshlrev_b32_e32 v1, 16, v1
	v_add_f32_e32 v0, v0, v1
	v_fma_f32 v3, v3, v0, -v1
	v_bfe_u32 v5, v3, 16, 1
	s_sub_i32 s1, s5, s1
	v_add3_u32 v3, v3, v5, s67
	s_add_i32 s1, s1, 1
	ds_write_b16_d16_hi v16, v3 offset:11392
	v_cvt_f32_i32_e32 v3, s1
	v_sub_f32_e32 v0, v0, v2
	ds_read_u16 v2, v16 offset:3456
	s_max_i32 s1, s4, 1
	v_rcp_iflag_f32_e32 v3, v3
	s_or_b32 s4, s0, 28
	s_min_i32 s5, s4, s25
	s_waitcnt lgkmcnt(0)
	v_lshlrev_b32_e32 v2, 16, v2
	v_add_f32_e32 v0, v0, v2
	v_fma_f32 v3, v3, v0, -v2
	v_bfe_u32 v5, v3, 16, 1
	s_sub_i32 s1, s5, s1
	v_add3_u32 v3, v3, v5, s67
	s_add_i32 s1, s1, 1
	ds_write_b16_d16_hi v16, v3 offset:11520
	v_cvt_f32_i32_e32 v3, s1
	v_sub_f32_e32 v0, v0, v1
	ds_read_u16 v1, v16 offset:3584
	s_max_i32 s1, s4, 1
	v_rcp_iflag_f32_e32 v3, v3
	s_or_b32 s4, s0, 29
	s_min_i32 s5, s4, s25
	s_waitcnt lgkmcnt(0)
	v_lshlrev_b32_e32 v1, 16, v1
	v_add_f32_e32 v0, v0, v1
	v_fma_f32 v3, v3, v0, -v1
	v_bfe_u32 v5, v3, 16, 1
	s_sub_i32 s1, s5, s1
	v_add3_u32 v3, v3, v5, s67
	s_add_i32 s1, s1, 1
	ds_write_b16_d16_hi v16, v3 offset:11648
	v_cvt_f32_i32_e32 v3, s1
	v_sub_f32_e32 v0, v0, v2
	ds_read_u16 v2, v16 offset:3712
	s_or_b32 s1, s0, 30
	v_rcp_iflag_f32_e32 v3, v3
	s_max_i32 s4, s4, 1
	s_min_i32 s5, s1, s25
	s_waitcnt lgkmcnt(0)
	v_lshlrev_b32_e32 v2, 16, v2
	v_add_f32_e32 v0, v0, v2
	v_fma_f32 v3, v3, v0, -v2
	v_bfe_u32 v5, v3, 16, 1
	s_sub_i32 s4, s5, s4
	v_add3_u32 v3, v3, v5, s67
	s_add_i32 s4, s4, 1
	ds_write_b16_d16_hi v16, v3 offset:11776
	v_cvt_f32_i32_e32 v3, s4
	v_sub_f32_e32 v0, v0, v1
	ds_read_u16 v1, v16 offset:3840
	s_or_b32 s4, s0, 31
	v_rcp_iflag_f32_e32 v3, v3
	s_max_i32 s1, s1, 1
	s_min_i32 s5, s4, s25
	s_waitcnt lgkmcnt(0)
	v_lshlrev_b32_e32 v1, 16, v1
	v_add_f32_e32 v0, v0, v1
	v_fma_f32 v3, v3, v0, -v1
	v_bfe_u32 v5, v3, 16, 1
	s_sub_i32 s1, s5, s1
	v_add3_u32 v3, v3, v5, s67
	s_add_i32 s1, s1, 1
	ds_write_b16_d16_hi v16, v3 offset:11904
	v_cvt_f32_i32_e32 v3, s1
	v_sub_f32_e32 v0, v0, v2
	ds_read_u16 v2, v16 offset:3968
	s_add_i32 s0, s0, 32
	v_rcp_iflag_f32_e32 v3, v3
	s_max_i32 s1, s4, 1
	s_min_i32 s0, s0, s25
	s_waitcnt lgkmcnt(0)
	v_lshlrev_b32_e32 v2, 16, v2
	v_add_f32_e32 v0, v0, v2
	v_fma_f32 v2, v3, v0, -v2
	v_bfe_u32 v3, v2, 16, 1
	s_sub_i32 s0, s0, s1
	v_add3_u32 v2, v2, v3, s67
	s_add_i32 s0, s0, 1
	ds_write_b16_d16_hi v16, v2 offset:12032
	v_cvt_f32_i32_e32 v2, s0
	v_sub_f32_e32 v0, v0, v1
	ds_read_u16 v1, v16 offset:4096
	v_or_b32_e32 v22, s24, v99
	v_rcp_iflag_f32_e32 v2, v2
	v_ashrrev_i32_e32 v23, 31, v22
	v_lshlrev_b64 v[22:23], 11, v[22:23]
	s_waitcnt lgkmcnt(0)
	v_lshlrev_b32_e32 v1, 16, v1
	v_add_f32_e32 v0, v0, v1
	v_fma_f32 v0, v2, v0, -v1
	v_bfe_u32 v1, v0, 16, 1
	v_add3_u32 v0, v0, v1, s67
	ds_write_b16_d16_hi v16, v0 offset:12160
	s_waitcnt lgkmcnt(0)
	ds_read_b128 v[0:3], v18 offset:8192
	v_lshl_add_u64 v[22:23], v[8:9], 0, v[22:23]
	v_or_b32_e32 v18, s24, v118
	s_waitcnt lgkmcnt(0)
	global_store_dwordx4 v[22:23], v[0:3], off
	ds_read_b128 v[0:3], v19 offset:8192
	v_ashrrev_i32_e32 v19, 31, v18
	v_lshlrev_b64 v[18:19], 11, v[18:19]
	v_lshl_add_u64 v[18:19], v[8:9], 0, v[18:19]
	s_waitcnt lgkmcnt(0)
	global_store_dwordx4 v[18:19], v[0:3], off
	ds_read_b128 v[0:3], v20 offset:8192
	v_or_b32_e32 v18, s24, v119
	v_ashrrev_i32_e32 v19, 31, v18
	v_lshlrev_b64 v[18:19], 11, v[18:19]
	v_lshl_add_u64 v[18:19], v[8:9], 0, v[18:19]
	s_waitcnt lgkmcnt(0)
	global_store_dwordx4 v[18:19], v[0:3], off
	ds_read_b128 v[0:3], v4 offset:8192
	v_or_b32_e32 v4, s24, v120
	v_ashrrev_i32_e32 v5, 31, v4
	v_lshlrev_b64 v[4:5], 11, v[4:5]
	v_lshl_add_u64 v[4:5], v[8:9], 0, v[4:5]
	s_waitcnt lgkmcnt(0)
	global_store_dwordx4 v[4:5], v[0:3], off
	s_waitcnt lgkmcnt(0)

.LBB0_498:
	s_or_b64 exec, exec, s[0:1]
	s_and_saveexec_b64 s[6:7], s[40:41]
	s_cbranch_execz .LBB0_502
	v_add_u32_e32 v5, s13, v121
	v_cmp_le_i32_e32 vcc, s26, v5
	v_cmp_gt_i32_e64 s[0:1], s27, v5
	s_and_b64 s[16:17], vcc, s[0:1]
	v_mov_b32_e32 v0, 0
	v_mov_b32_e32 v1, 0
	v_mov_b32_e32 v2, 0
	v_mov_b32_e32 v3, 0
	s_and_saveexec_b64 s[0:1], s[16:17]
	s_cbranch_execz .LBB0_501
	v_mad_i64_i32 v[0:1], s[16:17], v5, s53, v[6:7]
	global_load_dwordx4 v[0:3], v[0:1], off

.LBB0_502:
	s_or_b64 exec, exec, s[6:7]
	s_waitcnt vmcnt(0)
	v_add_u32_e32 v18, v10, v11
	ds_write_b128 v18, v[226:229]
	v_add_u32_e32 v19, v10, v12
	ds_write_b128 v19, v[230:233]
	v_add_u32_e32 v20, v10, v13
	ds_write_b128 v20, v[234:237]
	v_add_u32_e32 v4, v10, v14
	ds_write_b128 v4, v[238:241]
	s_waitcnt lgkmcnt(0)
	ds_read_u16 v0, v16
	ds_read_u16 v2, v16 offset:128
	ds_read_u16 v3, v16 offset:256
	ds_read_u16 v5, v16 offset:384
	ds_read_u16 v21, v16 offset:512
	ds_read_u16 v22, v16 offset:640
	ds_read_u16 v23, v16 offset:768
	ds_read_u16 v24, v16 offset:896
	s_sub_i32 s0, s24, s26
	s_or_b32 s6, s0, 4
	s_max_i32 s1, s0, 4
	s_min_i32 s7, s6, s25
	s_sub_i32 s1, s7, s1
	s_waitcnt lgkmcnt(7)
	v_lshlrev_b32_e32 v0, 16, v0
	s_add_i32 s1, s1, 4
	v_add_f32_e32 v1, 0, v0
	s_waitcnt lgkmcnt(6)
	v_lshlrev_b32_e32 v2, 16, v2
	v_cvt_f32_i32_e32 v25, s1
	v_add_f32_e32 v1, v1, v2
	s_waitcnt lgkmcnt(5)
	v_lshlrev_b32_e32 v3, 16, v3
	v_add_f32_e32 v1, v1, v3
	s_waitcnt lgkmcnt(4)
	v_lshlrev_b32_e32 v5, 16, v5
	v_add_f32_e32 v1, v1, v5
	s_waitcnt lgkmcnt(3)
	v_lshlrev_b32_e32 v21, 16, v21
	v_add_f32_e32 v1, v1, v21
	s_waitcnt lgkmcnt(2)
	v_lshlrev_b32_e32 v22, 16, v22
	v_rcp_iflag_f32_e32 v25, v25
	v_add_f32_e32 v1, v1, v22
	s_waitcnt lgkmcnt(1)
	v_lshlrev_b32_e32 v23, 16, v23
	v_add_f32_e32 v1, v1, v23
	s_waitcnt lgkmcnt(0)
	v_lshlrev_b32_e32 v24, 16, v24
	v_add_f32_e32 v1, v1, v24
	s_or_b32 s1, s0, 1
	s_or_b32 s16, s0, 5
	v_fma_f32 v21, v25, v1, -v21
	s_max_i32 s1, s1, 4
	s_min_i32 s7, s16, s25
	v_bfe_u32 v25, v21, 16, 1
	s_sub_i32 s1, s7, s1
	v_add3_u32 v21, v21, v25, s67
	s_add_i32 s1, s1, 4
	ds_write_b16_d16_hi v16, v21 offset:8192
	v_cvt_f32_i32_e32 v21, s1
	v_sub_f32_e32 v0, v1, v0
	ds_read_u16 v1, v16 offset:1024
	s_or_b32 s1, s0, 2
	v_rcp_iflag_f32_e32 v21, v21
	s_or_b32 s13, s0, 6
	s_max_i32 s1, s1, 4
	s_waitcnt lgkmcnt(0)
	v_lshlrev_b32_e32 v1, 16, v1
	v_add_f32_e32 v0, v0, v1
	v_fma_f32 v21, v21, v0, -v22
	s_min_i32 s7, s13, s25
	v_bfe_u32 v22, v21, 16, 1
	s_sub_i32 s1, s7, s1
	v_add3_u32 v21, v21, v22, s67
	s_add_i32 s1, s1, 4
	ds_write_b16_d16_hi v16, v21 offset:8320
	v_cvt_f32_i32_e32 v21, s1
	v_sub_f32_e32 v0, v0, v2
	ds_read_u16 v2, v16 offset:1152
	s_or_b32 s1, s0, 3
	v_rcp_iflag_f32_e32 v21, v21
	s_or_b32 s7, s0, 7
	s_max_i32 s1, s1, 4
	s_waitcnt lgkmcnt(0)
	v_lshlrev_b32_e32 v2, 16, v2
	v_add_f32_e32 v0, v0, v2
	v_fma_f32 v21, v21, v0, -v23
	s_min_i32 s17, s7, s25
	v_bfe_u32 v22, v21, 16, 1
	s_sub_i32 s1, s17, s1
	v_add3_u32 v21, v21, v22, s67
	s_add_i32 s1, s1, 4
	ds_write_b16_d16_hi v16, v21 offset:8448
	v_cvt_f32_i32_e32 v21, s1
	v_sub_f32_e32 v0, v0, v3
	ds_read_u16 v3, v16 offset:1280
	s_or_b32 s1, s0, 8
	v_rcp_iflag_f32_e32 v21, v21
	s_max_i32 s6, s6, 4
	s_min_i32 s17, s1, s25
	s_waitcnt lgkmcnt(0)
	v_lshlrev_b32_e32 v3, 16, v3
	v_add_f32_e32 v0, v0, v3
	v_fma_f32 v21, v21, v0, -v24
	v_bfe_u32 v22, v21, 16, 1
	s_sub_i32 s6, s17, s6
	v_add3_u32 v21, v21, v22, s67
	s_add_i32 s6, s6, 4
	ds_write_b16_d16_hi v16, v21 offset:8576
	v_cvt_f32_i32_e32 v21, s6
	v_sub_f32_e32 v0, v0, v5
	ds_read_u16 v5, v16 offset:1408
	s_or_b32 s6, s0, 9
	v_rcp_iflag_f32_e32 v21, v21
	s_max_i32 s16, s16, 4
	s_min_i32 s17, s6, s25
	s_waitcnt lgkmcnt(0)
	v_lshlrev_b32_e32 v5, 16, v5
	v_add_f32_e32 v0, v0, v5
	v_fma_f32 v1, v21, v0, -v1
	v_bfe_u32 v21, v1, 16, 1
	v_add3_u32 v1, v1, v21, s67
	ds_write_b16_d16_hi v16, v1 offset:8704
	ds_read_u16 v1, v16 offset:512
	s_sub_i32 s16, s17, s16
	s_add_i32 s16, s16, 4
	v_cvt_f32_i32_e32 v21, s16
	s_max_i32 s16, s13, 4
	s_waitcnt lgkmcnt(0)
	v_lshlrev_b32_e32 v1, 16, v1
	v_sub_f32_e32 v0, v0, v1
	ds_read_u16 v1, v16 offset:1536
	v_rcp_iflag_f32_e32 v21, v21
	s_or_b32 s13, s0, 10
	s_min_i32 s17, s13, s25
	s_sub_i32 s16, s17, s16
	s_waitcnt lgkmcnt(0)
	v_lshlrev_b32_e32 v1, 16, v1
	v_add_f32_e32 v0, v0, v1
	v_fma_f32 v2, v21, v0, -v2
	v_bfe_u32 v21, v2, 16, 1
	v_add3_u32 v2, v2, v21, s67
	ds_write_b16_d16_hi v16, v2 offset:8832
	ds_read_u16 v2, v16 offset:640
	s_add_i32 s16, s16, 4
	v_cvt_f32_i32_e32 v21, s16
	s_max_i32 s16, s7, 4
	s_or_b32 s7, s0, 11
	s_waitcnt lgkmcnt(0)
	v_lshlrev_b32_e32 v2, 16, v2
	v_sub_f32_e32 v0, v0, v2
	ds_read_u16 v2, v16 offset:1664
	v_rcp_iflag_f32_e32 v21, v21
	s_min_i32 s17, s7, s25
	s_sub_i32 s16, s17, s16
	s_add_i32 s16, s16, 4
	s_waitcnt lgkmcnt(0)
	v_lshlrev_b32_e32 v2, 16, v2
	v_add_f32_e32 v0, v0, v2
	v_fma_f32 v3, v21, v0, -v3
	v_bfe_u32 v21, v3, 16, 1
	v_add3_u32 v3, v3, v21, s67
	ds_write_b16_d16_hi v16, v3 offset:8960
	ds_read_u16 v3, v16 offset:768
	v_cvt_f32_i32_e32 v21, s16
	s_or_b32 s16, s0, 12
	s_max_i32 s1, s1, 4
	s_min_i32 s17, s16, s25
	s_waitcnt lgkmcnt(0)
	v_lshlrev_b32_e32 v3, 16, v3
	v_sub_f32_e32 v0, v0, v3
	ds_read_u16 v3, v16 offset:1792
	v_rcp_iflag_f32_e32 v21, v21
	s_sub_i32 s1, s17, s1
	s_add_i32 s1, s1, 4
	s_or_b32 s17, s0, 13
	s_waitcnt lgkmcnt(0)
	v_lshlrev_b32_e32 v3, 16, v3
	v_add_f32_e32 v0, v0, v3
	v_fma_f32 v5, v21, v0, -v5
	v_bfe_u32 v21, v5, 16, 1
	v_add3_u32 v5, v5, v21, s67
	ds_write_b16_d16_hi v16, v5 offset:9088
	ds_read_u16 v5, v16 offset:896
	v_cvt_f32_i32_e32 v21, s1
	s_max_i32 s1, s6, 4
	s_min_i32 s6, s17, s25
	s_sub_i32 s1, s6, s1
	s_waitcnt lgkmcnt(0)
	v_lshlrev_b32_e32 v5, 16, v5
	v_sub_f32_e32 v0, v0, v5
	ds_read_u16 v5, v16 offset:1920
	v_rcp_iflag_f32_e32 v21, v21
	s_add_i32 s1, s1, 4
	s_max_i32 s6, s13, 4
	s_max_i32 s7, s7, 4
	s_waitcnt lgkmcnt(0)
	v_lshlrev_b32_e32 v5, 16, v5
	v_add_f32_e32 v0, v0, v5
	v_fma_f32 v1, v21, v0, -v1
	v_bfe_u32 v21, v1, 16, 1
	v_add3_u32 v1, v1, v21, s67
	ds_write_b16_d16_hi v16, v1 offset:9216
	ds_read_u16 v1, v16 offset:1024
	v_cvt_f32_i32_e32 v21, s1
	s_or_b32 s1, s0, 14
	s_min_i32 s13, s1, s25
	s_sub_i32 s6, s13, s6
	s_waitcnt lgkmcnt(0)
	v_lshlrev_b32_e32 v1, 16, v1
	v_sub_f32_e32 v0, v0, v1
	ds_read_u16 v1, v16 offset:2048
	v_rcp_iflag_f32_e32 v21, v21
	s_add_i32 s6, s6, 4
	s_waitcnt lgkmcnt(0)
	v_lshlrev_b32_e32 v1, 16, v1
	v_add_f32_e32 v0, v0, v1
	v_fma_f32 v2, v21, v0, -v2
	v_bfe_u32 v21, v2, 16, 1
	v_add3_u32 v2, v2, v21, s67
	ds_write_b16_d16_hi v16, v2 offset:9344
	ds_read_u16 v2, v16 offset:1152
	v_cvt_f32_i32_e32 v21, s6
	s_or_b32 s6, s0, 15
	s_min_i32 s13, s6, s25
	s_sub_i32 s7, s13, s7
	s_waitcnt lgkmcnt(0)
	v_lshlrev_b32_e32 v2, 16, v2
	v_sub_f32_e32 v0, v0, v2
	ds_read_u16 v2, v16 offset:2176
	v_rcp_iflag_f32_e32 v21, v21
	s_add_i32 s7, s7, 4
	s_max_i32 s13, s16, 4
	s_waitcnt lgkmcnt(0)
	v_lshlrev_b32_e32 v2, 16, v2
	v_add_f32_e32 v0, v0, v2
	v_fma_f32 v3, v21, v0, -v3
	v_bfe_u32 v21, v3, 16, 1
	v_add3_u32 v3, v3, v21, s67
	ds_write_b16_d16_hi v16, v3 offset:9472
	ds_read_u16 v3, v16 offset:1280
	v_cvt_f32_i32_e32 v21, s7
	s_or_b32 s7, s0, 16
	s_min_i32 s16, s7, s25
	s_sub_i32 s13, s16, s13
	s_waitcnt lgkmcnt(0)
	v_lshlrev_b32_e32 v3, 16, v3
	v_sub_f32_e32 v0, v0, v3
	ds_read_u16 v3, v16 offset:2304
	v_rcp_iflag_f32_e32 v21, v21
	s_add_i32 s13, s13, 4
	s_max_i32 s16, s17, 4
	s_waitcnt lgkmcnt(0)
	v_lshlrev_b32_e32 v3, 16, v3
	v_add_f32_e32 v0, v0, v3
	v_fma_f32 v5, v21, v0, -v5
	v_bfe_u32 v21, v5, 16, 1
	v_add3_u32 v5, v5, v21, s67
	ds_write_b16_d16_hi v16, v5 offset:9600
	ds_read_u16 v5, v16 offset:1408
	v_cvt_f32_i32_e32 v21, s13
	s_or_b32 s13, s0, 17
	s_min_i32 s17, s13, s25
	s_sub_i32 s16, s17, s16
	s_waitcnt lgkmcnt(0)
	v_lshlrev_b32_e32 v5, 16, v5
	v_sub_f32_e32 v0, v0, v5
	ds_read_u16 v5, v16 offset:2432
	v_rcp_iflag_f32_e32 v21, v21
	s_add_i32 s16, s16, 4
	s_waitcnt lgkmcnt(0)
	v_lshlrev_b32_e32 v5, 16, v5
	v_add_f32_e32 v0, v0, v5
	v_fma_f32 v1, v21, v0, -v1
	v_bfe_u32 v21, v1, 16, 1
	v_add3_u32 v1, v1, v21, s67
	ds_write_b16_d16_hi v16, v1 offset:9728
	ds_read_u16 v1, v16 offset:1536
	v_cvt_f32_i32_e32 v21, s16
	s_max_i32 s16, s1, 4
	s_or_b32 s1, s0, 18
	s_min_i32 s17, s1, s25
	s_waitcnt lgkmcnt(0)
	v_lshlrev_b32_e32 v1, 16, v1
	v_sub_f32_e32 v0, v0, v1
	ds_read_u16 v1, v16 offset:2560
	v_rcp_iflag_f32_e32 v21, v21
	s_sub_i32 s16, s17, s16
	s_add_i32 s16, s16, 4
	s_waitcnt lgkmcnt(0)
	v_lshlrev_b32_e32 v1, 16, v1
	v_add_f32_e32 v0, v0, v1
	v_fma_f32 v2, v21, v0, -v2
	v_bfe_u32 v21, v2, 16, 1
	v_add3_u32 v2, v2, v21, s67
	ds_write_b16_d16_hi v16, v2 offset:9856
	ds_read_u16 v2, v16 offset:1664
	v_cvt_f32_i32_e32 v21, s16
	s_max_i32 s16, s6, 4
	s_or_b32 s6, s0, 19
	s_min_i32 s17, s6, s25
	s_waitcnt lgkmcnt(0)
	v_lshlrev_b32_e32 v2, 16, v2
	v_sub_f32_e32 v0, v0, v2
	ds_read_u16 v2, v16 offset:2688
	v_rcp_iflag_f32_e32 v21, v21
	s_sub_i32 s16, s17, s16
	s_add_i32 s16, s16, 4
	s_waitcnt lgkmcnt(0)
	v_lshlrev_b32_e32 v2, 16, v2
	v_add_f32_e32 v0, v0, v2
	v_fma_f32 v3, v21, v0, -v3
	v_bfe_u32 v21, v3, 16, 1
	v_add3_u32 v3, v3, v21, s67
	ds_write_b16_d16_hi v16, v3 offset:9984
	ds_read_u16 v3, v16 offset:1792
	v_cvt_f32_i32_e32 v21, s16
	s_max_i32 s16, s7, 4
	s_or_b32 s7, s0, 20
	s_min_i32 s17, s7, s25
	s_waitcnt lgkmcnt(0)
	v_lshlrev_b32_e32 v3, 16, v3
	v_sub_f32_e32 v0, v0, v3
	ds_read_u16 v3, v16 offset:2816
	v_rcp_iflag_f32_e32 v21, v21
	s_sub_i32 s16, s17, s16
	s_add_i32 s16, s16, 4
	s_waitcnt lgkmcnt(0)
	v_lshlrev_b32_e32 v3, 16, v3
	v_add_f32_e32 v0, v0, v3
	v_fma_f32 v5, v21, v0, -v5
	v_bfe_u32 v21, v5, 16, 1
	v_add3_u32 v5, v5, v21, s67
	ds_write_b16_d16_hi v16, v5 offset:10112
	ds_read_u16 v5, v16 offset:1920
	v_cvt_f32_i32_e32 v21, s16
	s_max_i32 s16, s13, 4
	s_or_b32 s13, s0, 21
	s_min_i32 s17, s13, s25
	s_waitcnt lgkmcnt(0)
	v_lshlrev_b32_e32 v5, 16, v5
	v_sub_f32_e32 v0, v0, v5
	ds_read_u16 v5, v16 offset:2944
	v_rcp_iflag_f32_e32 v21, v21
	s_sub_i32 s16, s17, s16
	s_add_i32 s16, s16, 4
	s_waitcnt lgkmcnt(0)
	v_lshlrev_b32_e32 v5, 16, v5
	v_add_f32_e32 v0, v0, v5
	v_fma_f32 v1, v21, v0, -v1
	v_bfe_u32 v21, v1, 16, 1
	v_add3_u32 v1, v1, v21, s67
	ds_write_b16_d16_hi v16, v1 offset:10240
	ds_read_u16 v1, v16 offset:2048
	s_waitcnt lgkmcnt(0)
	v_lshlrev_b32_e32 v1, 16, v1
	v_sub_f32_e32 v0, v0, v1
	ds_read_u16 v1, v16 offset:3072
	s_waitcnt lgkmcnt(0)
	v_lshlrev_b32_e32 v21, 16, v1
	v_cvt_f32_i32_e32 v1, s16
	v_add_f32_e32 v0, v0, v21
	s_max_i32 s16, s1, 4
	s_or_b32 s1, s0, 22
	v_rcp_iflag_f32_e32 v1, v1
	s_min_i32 s17, s1, s25
	s_sub_i32 s16, s17, s16
	s_add_i32 s16, s16, 4
	v_fma_f32 v1, v1, v0, -v2
	v_bfe_u32 v2, v1, 16, 1
	v_add3_u32 v1, v1, v2, s67
	ds_write_b16_d16_hi v16, v1 offset:10368
	ds_read_u16 v1, v16 offset:2176
	s_waitcnt lgkmcnt(0)
	v_lshlrev_b32_e32 v1, 16, v1
	v_sub_f32_e32 v0, v0, v1
	ds_read_u16 v1, v16 offset:3200
	s_waitcnt lgkmcnt(0)
	v_lshlrev_b32_e32 v22, 16, v1
	v_cvt_f32_i32_e32 v1, s16
	v_add_f32_e32 v0, v0, v22
	s_max_i32 s16, s6, 4
	s_or_b32 s6, s0, 23
	v_rcp_iflag_f32_e32 v1, v1
	s_min_i32 s17, s6, s25
	s_sub_i32 s16, s17, s16
	s_add_i32 s16, s16, 4
	v_fma_f32 v1, v1, v0, -v3
	v_bfe_u32 v2, v1, 16, 1
	v_add3_u32 v1, v1, v2, s67
	ds_write_b16_d16_hi v16, v1 offset:10496
	ds_read_u16 v1, v16 offset:2304
	v_cvt_f32_i32_e32 v2, s16
	s_max_i32 s16, s7, 4
	s_or_b32 s7, s0, 24
	s_min_i32 s17, s7, s25
	s_waitcnt lgkmcnt(0)
	v_lshlrev_b32_e32 v1, 16, v1
	v_sub_f32_e32 v1, v0, v1
	ds_read_u16 v0, v16 offset:3328
	v_rcp_iflag_f32_e32 v2, v2
	s_sub_i32 s16, s17, s16
	s_add_i32 s16, s16, 4
	s_waitcnt lgkmcnt(0)
	v_lshlrev_b32_e32 v0, 16, v0
	v_add_f32_e32 v1, v1, v0
	v_fma_f32 v2, v2, v1, -v5
	v_bfe_u32 v3, v2, 16, 1
	v_add3_u32 v2, v2, v3, s67
	ds_write_b16_d16_hi v16, v2 offset:10624
	ds_read_u16 v2, v16 offset:2432
	v_cvt_f32_i32_e32 v3, s16
	s_max_i32 s16, s13, 4
	s_or_b32 s13, s0, 25
	s_min_i32 s17, s13, s25
	s_waitcnt lgkmcnt(0)
	v_lshlrev_b32_e32 v2, 16, v2
	v_sub_f32_e32 v2, v1, v2
	ds_read_u16 v1, v16 offset:3456
	v_rcp_iflag_f32_e32 v3, v3
	s_sub_i32 s16, s17, s16
	s_add_i32 s16, s16, 4
	s_waitcnt lgkmcnt(0)
	v_lshlrev_b32_e32 v1, 16, v1
	v_add_f32_e32 v2, v2, v1
	v_fma_f32 v3, v3, v2, -v21
	v_bfe_u32 v5, v3, 16, 1
	v_add3_u32 v3, v3, v5, s67
	ds_write_b16_d16_hi v16, v3 offset:10752
	ds_read_u16 v3, v16 offset:2560
	v_cvt_f32_i32_e32 v5, s16
	s_max_i32 s16, s1, 4
	s_or_b32 s1, s0, 26
	s_min_i32 s17, s1, s25
	s_waitcnt lgkmcnt(0)
	v_lshlrev_b32_e32 v3, 16, v3
	v_sub_f32_e32 v3, v2, v3
	ds_read_u16 v2, v16 offset:3584
	v_rcp_iflag_f32_e32 v5, v5
	s_sub_i32 s16, s17, s16
	s_add_i32 s16, s16, 4
	s_max_i32 s1, s1, 4
	s_waitcnt lgkmcnt(0)
	v_lshlrev_b32_e32 v2, 16, v2
	v_add_f32_e32 v3, v3, v2
	v_fma_f32 v5, v5, v3, -v22
	v_bfe_u32 v21, v5, 16, 1
	v_add3_u32 v5, v5, v21, s67
	ds_write_b16_d16_hi v16, v5 offset:10880
	ds_read_u16 v5, v16 offset:2688
	v_cvt_f32_i32_e32 v21, s16
	s_max_i32 s16, s6, 4
	s_or_b32 s6, s0, 27
	s_min_i32 s17, s6, s25
	s_waitcnt lgkmcnt(0)
	v_lshlrev_b32_e32 v5, 16, v5
	v_sub_f32_e32 v3, v3, v5
	ds_read_u16 v5, v16 offset:3712
	v_rcp_iflag_f32_e32 v21, v21
	s_sub_i32 s16, s17, s16
	s_add_i32 s16, s16, 4
	s_max_i32 s6, s6, 4
	s_waitcnt lgkmcnt(0)
	v_lshlrev_b32_e32 v5, 16, v5
	v_add_f32_e32 v3, v3, v5
	v_fma_f32 v0, v21, v3, -v0
	v_bfe_u32 v21, v0, 16, 1
	v_add3_u32 v0, v0, v21, s67
	ds_write_b16_d16_hi v16, v0 offset:11008
	ds_read_u16 v0, v16 offset:2816
	v_cvt_f32_i32_e32 v21, s16
	s_max_i32 s16, s7, 4
	s_or_b32 s7, s0, 28
	s_min_i32 s17, s7, s25
	s_waitcnt lgkmcnt(0)
	v_lshlrev_b32_e32 v0, 16, v0
	v_sub_f32_e32 v3, v3, v0
	ds_read_u16 v0, v16 offset:3840
	v_rcp_iflag_f32_e32 v21, v21
	s_sub_i32 s16, s17, s16
	s_add_i32 s16, s16, 4
	v_or_b32_e32 v22, s24, v99
	s_waitcnt lgkmcnt(0)
	v_lshlrev_b32_e32 v0, 16, v0
	v_add_f32_e32 v3, v3, v0
	v_fma_f32 v1, v21, v3, -v1
	v_bfe_u32 v21, v1, 16, 1
	v_add3_u32 v1, v1, v21, s67
	ds_write_b16_d16_hi v16, v1 offset:11136
	ds_read_u16 v1, v16 offset:2944
	v_cvt_f32_i32_e32 v21, s16
	s_max_i32 s16, s13, 4
	s_or_b32 s13, s0, 29
	s_min_i32 s17, s13, s25
	s_waitcnt lgkmcnt(0)
	v_lshlrev_b32_e32 v1, 16, v1
	v_sub_f32_e32 v3, v3, v1
	ds_read_u16 v1, v16 offset:3968
	v_rcp_iflag_f32_e32 v21, v21
	s_sub_i32 s16, s17, s16
	s_add_i32 s16, s16, 4
	v_ashrrev_i32_e32 v23, 31, v22
	s_waitcnt lgkmcnt(0)
	v_lshlrev_b32_e32 v1, 16, v1
	v_add_f32_e32 v3, v3, v1
	v_fma_f32 v2, v21, v3, -v2
	v_bfe_u32 v21, v2, 16, 1
	v_add3_u32 v2, v2, v21, s67
	ds_write_b16_d16_hi v16, v2 offset:11264
	ds_read_u16 v2, v16 offset:3072
	v_cvt_f32_i32_e32 v21, s16
	s_or_b32 s16, s0, 30
	s_min_i32 s17, s16, s25
	s_sub_i32 s1, s17, s1
	s_waitcnt lgkmcnt(0)
	v_lshlrev_b32_e32 v2, 16, v2
	v_sub_f32_e32 v3, v3, v2
	ds_read_u16 v2, v16 offset:4096
	v_rcp_iflag_f32_e32 v21, v21
	s_add_i32 s1, s1, 4
	v_lshlrev_b64 v[22:23], 11, v[22:23]
	v_lshl_add_u64 v[22:23], v[8:9], 0, v[22:23]
	s_waitcnt lgkmcnt(0)
	v_lshlrev_b32_e32 v2, 16, v2
	v_add_f32_e32 v3, v3, v2
	v_fma_f32 v5, v21, v3, -v5
	v_bfe_u32 v21, v5, 16, 1
	v_add3_u32 v5, v5, v21, s67
	ds_write_b16_d16_hi v16, v5 offset:11392
	ds_read_u16 v5, v16 offset:3200
	v_cvt_f32_i32_e32 v21, s1
	s_or_b32 s1, s0, 31
	s_min_i32 s17, s1, s25
	s_sub_i32 s6, s17, s6
	s_waitcnt lgkmcnt(0)
	v_lshlrev_b32_e32 v5, 16, v5
	v_sub_f32_e32 v3, v3, v5
	ds_read_u16 v5, v16 offset:4224
	v_rcp_iflag_f32_e32 v21, v21
	s_add_i32 s6, s6, 4
	s_max_i32 s1, s1, 4
	s_waitcnt lgkmcnt(0)
	v_lshlrev_b32_e32 v5, 16, v5
	v_add_f32_e32 v3, v3, v5
	v_fma_f32 v0, v21, v3, -v0
	v_bfe_u32 v21, v0, 16, 1
	v_add3_u32 v0, v0, v21, s67
	ds_write_b16_d16_hi v16, v0 offset:11520
	ds_read_u16 v0, v16 offset:3328
	v_cvt_f32_i32_e32 v21, s6
	s_max_i32 s6, s7, 4
	s_add_i32 s7, s0, 32
	s_min_i32 s7, s7, s25
	s_waitcnt lgkmcnt(0)
	v_lshlrev_b32_e32 v0, 16, v0
	v_sub_f32_e32 v0, v3, v0
	ds_read_u16 v3, v16 offset:4352
	v_rcp_iflag_f32_e32 v21, v21
	s_sub_i32 s6, s7, s6
	s_add_i32 s6, s6, 4
	s_add_i32 s7, s0, 33
	s_waitcnt lgkmcnt(0)
	v_lshlrev_b32_e32 v3, 16, v3
	v_add_f32_e32 v0, v0, v3
	v_fma_f32 v1, v21, v0, -v1
	v_bfe_u32 v21, v1, 16, 1
	v_add3_u32 v1, v1, v21, s67
	ds_write_b16_d16_hi v16, v1 offset:11648
	ds_read_u16 v1, v16 offset:3456
	v_cvt_f32_i32_e32 v21, s6
	s_max_i32 s6, s13, 4
	s_min_i32 s7, s7, s25
	s_sub_i32 s6, s7, s6
	s_waitcnt lgkmcnt(0)
	v_lshlrev_b32_e32 v1, 16, v1
	v_sub_f32_e32 v1, v0, v1
	ds_read_u16 v0, v16 offset:4480
	v_rcp_iflag_f32_e32 v21, v21
	s_add_i32 s6, s6, 4
	s_add_i32 s7, s0, 34
	s_min_i32 s7, s7, s25
	s_waitcnt lgkmcnt(0)
	v_lshlrev_b32_e32 v0, 16, v0
	v_add_f32_e32 v1, v1, v0
	v_fma_f32 v2, v21, v1, -v2
	v_bfe_u32 v21, v2, 16, 1
	v_add3_u32 v2, v2, v21, s67
	ds_write_b16_d16_hi v16, v2 offset:11776
	ds_read_u16 v2, v16 offset:3584
	s_add_i32 s0, s0, 35
	s_min_i32 s0, s0, s25
	s_sub_i32 s0, s0, s1
	s_add_i32 s0, s0, 4
	s_waitcnt lgkmcnt(0)
	v_lshlrev_b32_e32 v2, 16, v2
	v_sub_f32_e32 v1, v1, v2
	ds_read_u16 v2, v16 offset:4608
	s_waitcnt lgkmcnt(0)
	v_lshlrev_b32_e32 v2, 16, v2
	v_add_f32_e32 v1, v1, v2
	v_cvt_f32_i32_e32 v2, s6
	s_max_i32 s6, s16, 4
	s_sub_i32 s6, s7, s6
	s_add_i32 s6, s6, 4
	v_rcp_iflag_f32_e32 v2, v2
	s_nop 0
	v_fma_f32 v2, v2, v1, -v5
	v_bfe_u32 v5, v2, 16, 1
	v_add3_u32 v2, v2, v5, s67
	ds_write_b16_d16_hi v16, v2 offset:11904
	ds_read_u16 v2, v16 offset:3712
	s_waitcnt lgkmcnt(0)
	v_lshlrev_b32_e32 v2, 16, v2
	v_sub_f32_e32 v1, v1, v2
	ds_read_u16 v2, v16 offset:4736
	s_waitcnt lgkmcnt(0)
	v_lshlrev_b32_e32 v2, 16, v2
	v_add_f32_e32 v1, v1, v2
	v_cvt_f32_i32_e32 v2, s6
	s_mov_b64 s[6:7], 0
	v_rcp_iflag_f32_e32 v2, v2
	s_nop 0
	v_fma_f32 v2, v2, v1, -v3
	v_bfe_u32 v3, v2, 16, 1
	v_add3_u32 v2, v2, v3, s67
	ds_write_b16_d16_hi v16, v2 offset:12032
	ds_read_u16 v2, v16 offset:3840
	s_waitcnt lgkmcnt(0)
	v_lshlrev_b32_e32 v2, 16, v2
	v_sub_f32_e32 v1, v1, v2
	ds_read_u16 v2, v16 offset:4864
	s_waitcnt lgkmcnt(0)
	v_lshlrev_b32_e32 v2, 16, v2
	v_add_f32_e32 v1, v1, v2
	v_cvt_f32_i32_e32 v2, s0
	v_rcp_iflag_f32_e32 v2, v2
	s_nop 0
	v_fma_f32 v0, v2, v1, -v0
	v_bfe_u32 v1, v0, 16, 1
	v_add3_u32 v0, v0, v1, s67
	ds_write_b16_d16_hi v16, v0 offset:12160
	s_waitcnt lgkmcnt(0)
	ds_read_b128 v[0:3], v18 offset:8192
	v_or_b32_e32 v18, s24, v118
	s_waitcnt lgkmcnt(0)
	global_store_dwordx4 v[22:23], v[0:3], off
	ds_read_b128 v[0:3], v19 offset:8192
	v_ashrrev_i32_e32 v19, 31, v18
	v_lshlrev_b64 v[18:19], 11, v[18:19]
	v_lshl_add_u64 v[18:19], v[8:9], 0, v[18:19]
	s_waitcnt lgkmcnt(0)
	global_store_dwordx4 v[18:19], v[0:3], off
	ds_read_b128 v[0:3], v20 offset:8192
	v_or_b32_e32 v18, s24, v119
	v_ashrrev_i32_e32 v19, 31, v18
	v_lshlrev_b64 v[18:19], 11, v[18:19]
	v_lshl_add_u64 v[18:19], v[8:9], 0, v[18:19]
	s_waitcnt lgkmcnt(0)
	global_store_dwordx4 v[18:19], v[0:3], off
	ds_read_b128 v[0:3], v4 offset:8192
	v_or_b32_e32 v4, s24, v120
	v_ashrrev_i32_e32 v5, 31, v4
	v_lshlrev_b64 v[4:5], 11, v[4:5]
	v_lshl_add_u64 v[4:5], v[8:9], 0, v[4:5]
	s_waitcnt lgkmcnt(0)
	global_store_dwordx4 v[4:5], v[0:3], off
	s_waitcnt lgkmcnt(0)

.LBB0_513:
	s_or_b64 exec, exec, s[0:1]
	s_and_saveexec_b64 s[16:17], s[42:43]
	s_cbranch_execz .LBB0_517
	v_add_u32_e32 v5, s13, v121
	v_cmp_le_i32_e32 vcc, s26, v5
	v_cmp_gt_i32_e64 s[0:1], s27, v5
	s_and_b64 s[28:29], vcc, s[0:1]
	v_mov_b32_e32 v0, 0
	v_mov_b32_e32 v1, 0
	v_mov_b32_e32 v2, 0
	v_mov_b32_e32 v3, 0
	s_and_saveexec_b64 s[0:1], s[28:29]
	s_cbranch_execz .LBB0_516
	v_mad_i64_i32 v[0:1], s[28:29], v5, s53, v[6:7]
	global_load_dwordx4 v[0:3], v[0:1], off

.LBB0_517:
	s_or_b64 exec, exec, s[16:17]
	s_waitcnt vmcnt(0)
	v_add_u32_e32 v18, v10, v11
	ds_write_b128 v18, v[226:229]
	v_add_u32_e32 v19, v10, v12
	ds_write_b128 v19, v[230:233]
	v_add_u32_e32 v20, v10, v13
	ds_write_b128 v20, v[234:237]
	v_add_u32_e32 v4, v10, v14
	ds_write_b128 v4, v[238:241]
	s_sub_i32 s0, s24, s26
	s_or_b32 s13, s0, 2
	s_waitcnt lgkmcnt(0)
	s_max_i32 s1, s0, 2
	s_min_i32 s16, s13, s25
	ds_read_u16 v0, v16
	ds_read_u16 v2, v16 offset:128
	ds_read_u16 v3, v16 offset:256
	ds_read_u16 v5, v16 offset:384
	s_sub_i32 s1, s16, s1
	s_add_i32 s1, s1, 2
	v_cvt_f32_i32_e32 v21, s1
	s_waitcnt lgkmcnt(3)
	v_lshlrev_b32_e32 v0, 16, v0
	v_add_f32_e32 v1, 0, v0
	s_waitcnt lgkmcnt(2)
	v_lshlrev_b32_e32 v2, 16, v2
	v_rcp_iflag_f32_e32 v21, v21
	v_add_f32_e32 v1, v1, v2
	s_waitcnt lgkmcnt(1)
	v_lshlrev_b32_e32 v3, 16, v3
	v_add_f32_e32 v1, v1, v3
	s_waitcnt lgkmcnt(0)
	v_lshlrev_b32_e32 v5, 16, v5
	v_add_f32_e32 v1, v1, v5
	s_or_b32 s1, s0, 1
	s_or_b32 s16, s0, 3
	v_fma_f32 v21, v21, v1, -v3
	s_max_i32 s1, s1, 2
	s_min_i32 s17, s16, s25
	v_bfe_u32 v22, v21, 16, 1
	s_sub_i32 s1, s17, s1
	v_add3_u32 v21, v21, v22, s67
	s_add_i32 s1, s1, 2
	ds_write_b16_d16_hi v16, v21 offset:8192
	v_cvt_f32_i32_e32 v21, s1
	v_sub_f32_e32 v0, v1, v0
	ds_read_u16 v1, v16 offset:512
	s_or_b32 s1, s0, 4
	v_rcp_iflag_f32_e32 v21, v21
	s_max_i32 s13, s13, 2
	s_min_i32 s17, s1, s25
	s_waitcnt lgkmcnt(0)
	v_lshlrev_b32_e32 v1, 16, v1
	v_add_f32_e32 v0, v0, v1
	v_fma_f32 v21, v21, v0, -v5
	v_bfe_u32 v22, v21, 16, 1
	s_sub_i32 s13, s17, s13
	v_add3_u32 v21, v21, v22, s67
	s_add_i32 s13, s13, 2
	ds_write_b16_d16_hi v16, v21 offset:8320
	v_cvt_f32_i32_e32 v21, s13
	v_sub_f32_e32 v0, v0, v2
	ds_read_u16 v2, v16 offset:640
	s_or_b32 s13, s0, 5
	v_rcp_iflag_f32_e32 v21, v21
	s_max_i32 s16, s16, 2
	s_min_i32 s17, s13, s25
	s_waitcnt lgkmcnt(0)
	v_lshlrev_b32_e32 v2, 16, v2
	v_add_f32_e32 v0, v0, v2
	v_fma_f32 v21, v21, v0, -v1
	v_bfe_u32 v22, v21, 16, 1
	s_sub_i32 s16, s17, s16
	v_add3_u32 v21, v21, v22, s67
	s_add_i32 s16, s16, 2
	ds_write_b16_d16_hi v16, v21 offset:8448
	v_cvt_f32_i32_e32 v21, s16
	v_sub_f32_e32 v0, v0, v3
	ds_read_u16 v3, v16 offset:768
	s_or_b32 s16, s0, 6
	v_rcp_iflag_f32_e32 v21, v21
	s_max_i32 s1, s1, 2
	s_min_i32 s17, s16, s25
	s_waitcnt lgkmcnt(0)
	v_lshlrev_b32_e32 v3, 16, v3
	v_add_f32_e32 v0, v0, v3
	v_fma_f32 v21, v21, v0, -v2
	v_bfe_u32 v22, v21, 16, 1
	s_sub_i32 s1, s17, s1
	v_add3_u32 v21, v21, v22, s67
	s_add_i32 s1, s1, 2
	ds_write_b16_d16_hi v16, v21 offset:8576
	v_cvt_f32_i32_e32 v21, s1
	v_sub_f32_e32 v0, v0, v5
	ds_read_u16 v5, v16 offset:896
	s_max_i32 s1, s13, 2
	v_rcp_iflag_f32_e32 v21, v21
	s_or_b32 s13, s0, 7
	s_min_i32 s17, s13, s25
	s_waitcnt lgkmcnt(0)
	v_lshlrev_b32_e32 v5, 16, v5
	v_add_f32_e32 v0, v0, v5
	v_fma_f32 v21, v21, v0, -v3
	v_bfe_u32 v22, v21, 16, 1
	s_sub_i32 s1, s17, s1
	v_add3_u32 v21, v21, v22, s67
	s_add_i32 s1, s1, 2
	ds_write_b16_d16_hi v16, v21 offset:8704
	v_cvt_f32_i32_e32 v21, s1
	v_sub_f32_e32 v0, v0, v1
	ds_read_u16 v1, v16 offset:1024
	s_max_i32 s1, s16, 2
	v_rcp_iflag_f32_e32 v21, v21
	s_or_b32 s16, s0, 8
	s_min_i32 s17, s16, s25
	s_waitcnt lgkmcnt(0)
	v_lshlrev_b32_e32 v1, 16, v1
	v_add_f32_e32 v0, v0, v1
	v_fma_f32 v21, v21, v0, -v5
	v_bfe_u32 v22, v21, 16, 1
	s_sub_i32 s1, s17, s1
	v_add3_u32 v21, v21, v22, s67
	s_add_i32 s1, s1, 2
	ds_write_b16_d16_hi v16, v21 offset:8832
	v_cvt_f32_i32_e32 v21, s1
	v_sub_f32_e32 v0, v0, v2
	ds_read_u16 v2, v16 offset:1152
	s_max_i32 s1, s13, 2
	v_rcp_iflag_f32_e32 v21, v21
	s_or_b32 s13, s0, 9
	s_min_i32 s17, s13, s25
	s_waitcnt lgkmcnt(0)
	v_lshlrev_b32_e32 v2, 16, v2
	v_add_f32_e32 v0, v0, v2
	v_fma_f32 v21, v21, v0, -v1
	v_bfe_u32 v22, v21, 16, 1
	s_sub_i32 s1, s17, s1
	v_add3_u32 v21, v21, v22, s67
	s_add_i32 s1, s1, 2
	ds_write_b16_d16_hi v16, v21 offset:8960
	v_cvt_f32_i32_e32 v21, s1
	v_sub_f32_e32 v0, v0, v3
	ds_read_u16 v3, v16 offset:1280
	s_max_i32 s1, s16, 2
	v_rcp_iflag_f32_e32 v21, v21
	s_or_b32 s16, s0, 10
	s_min_i32 s17, s16, s25
	s_waitcnt lgkmcnt(0)
	v_lshlrev_b32_e32 v3, 16, v3
	v_add_f32_e32 v0, v0, v3
	v_fma_f32 v21, v21, v0, -v2
	v_bfe_u32 v22, v21, 16, 1
	s_sub_i32 s1, s17, s1
	v_add3_u32 v21, v21, v22, s67
	s_add_i32 s1, s1, 2
	ds_write_b16_d16_hi v16, v21 offset:9088
	v_cvt_f32_i32_e32 v21, s1
	v_sub_f32_e32 v0, v0, v5
	ds_read_u16 v5, v16 offset:1408
	s_max_i32 s1, s13, 2
	v_rcp_iflag_f32_e32 v21, v21
	s_or_b32 s13, s0, 11
	s_min_i32 s17, s13, s25
	s_waitcnt lgkmcnt(0)
	v_lshlrev_b32_e32 v5, 16, v5
	v_add_f32_e32 v0, v0, v5
	v_fma_f32 v21, v21, v0, -v3
	v_bfe_u32 v22, v21, 16, 1
	s_sub_i32 s1, s17, s1
	v_add3_u32 v21, v21, v22, s67
	s_add_i32 s1, s1, 2
	ds_write_b16_d16_hi v16, v21 offset:9216
	v_cvt_f32_i32_e32 v21, s1
	v_sub_f32_e32 v1, v0, v1
	ds_read_u16 v0, v16 offset:1536
	s_or_b32 s1, s0, 12
	v_rcp_iflag_f32_e32 v21, v21
	s_max_i32 s16, s16, 2
	s_min_i32 s17, s1, s25
	s_waitcnt lgkmcnt(0)
	v_lshlrev_b32_e32 v0, 16, v0
	v_add_f32_e32 v1, v1, v0
	v_fma_f32 v21, v21, v1, -v5
	v_bfe_u32 v22, v21, 16, 1
	s_sub_i32 s16, s17, s16
	v_add3_u32 v21, v21, v22, s67
	s_add_i32 s16, s16, 2
	ds_write_b16_d16_hi v16, v21 offset:9344
	v_cvt_f32_i32_e32 v21, s16
	v_sub_f32_e32 v2, v1, v2
	ds_read_u16 v1, v16 offset:1664
	s_max_i32 s16, s13, 2
	v_rcp_iflag_f32_e32 v21, v21
	s_or_b32 s13, s0, 13
	s_min_i32 s17, s13, s25
	s_waitcnt lgkmcnt(0)
	v_lshlrev_b32_e32 v1, 16, v1
	v_add_f32_e32 v2, v2, v1
	v_fma_f32 v21, v21, v2, -v0
	v_bfe_u32 v22, v21, 16, 1
	s_sub_i32 s16, s17, s16
	v_add3_u32 v21, v21, v22, s67
	s_add_i32 s16, s16, 2
	ds_write_b16_d16_hi v16, v21 offset:9472
	v_cvt_f32_i32_e32 v21, s16
	v_sub_f32_e32 v2, v2, v3
	ds_read_u16 v3, v16 offset:1792
	s_or_b32 s16, s0, 14
	v_rcp_iflag_f32_e32 v21, v21
	s_max_i32 s1, s1, 2
	s_min_i32 s17, s16, s25
	s_waitcnt lgkmcnt(0)
	v_lshlrev_b32_e32 v3, 16, v3
	v_add_f32_e32 v2, v2, v3
	v_fma_f32 v21, v21, v2, -v1
	v_bfe_u32 v22, v21, 16, 1
	s_sub_i32 s1, s17, s1
	v_add3_u32 v21, v21, v22, s67
	s_add_i32 s1, s1, 2
	ds_write_b16_d16_hi v16, v21 offset:9600
	v_cvt_f32_i32_e32 v21, s1
	v_sub_f32_e32 v2, v2, v5
	ds_read_u16 v5, v16 offset:1920
	s_max_i32 s1, s13, 2
	v_rcp_iflag_f32_e32 v21, v21
	s_or_b32 s13, s0, 15
	s_min_i32 s17, s13, s25
	s_waitcnt lgkmcnt(0)
	v_lshlrev_b32_e32 v5, 16, v5
	v_add_f32_e32 v2, v2, v5
	v_fma_f32 v21, v21, v2, -v3
	v_bfe_u32 v22, v21, 16, 1
	s_sub_i32 s1, s17, s1
	v_add3_u32 v21, v21, v22, s67
	s_add_i32 s1, s1, 2
	ds_write_b16_d16_hi v16, v21 offset:9728
	v_cvt_f32_i32_e32 v21, s1
	v_sub_f32_e32 v0, v2, v0
	ds_read_u16 v2, v16 offset:2048
	s_max_i32 s1, s16, 2
	v_rcp_iflag_f32_e32 v21, v21
	s_or_b32 s16, s0, 16
	s_min_i32 s17, s16, s25
	s_waitcnt lgkmcnt(0)
	v_lshlrev_b32_e32 v2, 16, v2
	v_add_f32_e32 v0, v0, v2
	v_fma_f32 v21, v21, v0, -v5
	v_bfe_u32 v22, v21, 16, 1
	s_sub_i32 s1, s17, s1
	v_add3_u32 v21, v21, v22, s67
	s_add_i32 s1, s1, 2
	ds_write_b16_d16_hi v16, v21 offset:9856
	v_cvt_f32_i32_e32 v21, s1
	v_sub_f32_e32 v0, v0, v1
	ds_read_u16 v1, v16 offset:2176
	s_max_i32 s1, s13, 2
	v_rcp_iflag_f32_e32 v21, v21
	s_or_b32 s13, s0, 17
	s_min_i32 s17, s13, s25
	s_waitcnt lgkmcnt(0)
	v_lshlrev_b32_e32 v1, 16, v1
	v_add_f32_e32 v0, v0, v1
	v_fma_f32 v21, v21, v0, -v2
	v_bfe_u32 v22, v21, 16, 1
	s_sub_i32 s1, s17, s1
	v_add3_u32 v21, v21, v22, s67
	s_add_i32 s1, s1, 2
	ds_write_b16_d16_hi v16, v21 offset:9984
	v_cvt_f32_i32_e32 v21, s1
	v_sub_f32_e32 v0, v0, v3
	ds_read_u16 v3, v16 offset:2304
	s_max_i32 s1, s16, 2
	v_rcp_iflag_f32_e32 v21, v21
	s_or_b32 s16, s0, 18
	s_min_i32 s17, s16, s25
	s_waitcnt lgkmcnt(0)
	v_lshlrev_b32_e32 v3, 16, v3
	v_add_f32_e32 v0, v0, v3
	v_fma_f32 v21, v21, v0, -v1
	v_bfe_u32 v22, v21, 16, 1
	s_sub_i32 s1, s17, s1
	v_add3_u32 v21, v21, v22, s67
	s_add_i32 s1, s1, 2
	ds_write_b16_d16_hi v16, v21 offset:10112
	v_cvt_f32_i32_e32 v21, s1
	v_sub_f32_e32 v0, v0, v5
	ds_read_u16 v5, v16 offset:2432
	s_max_i32 s1, s13, 2
	v_rcp_iflag_f32_e32 v21, v21
	s_or_b32 s13, s0, 19
	s_min_i32 s17, s13, s25
	s_waitcnt lgkmcnt(0)
	v_lshlrev_b32_e32 v5, 16, v5
	v_add_f32_e32 v0, v0, v5
	v_fma_f32 v21, v21, v0, -v3
	v_bfe_u32 v22, v21, 16, 1
	s_sub_i32 s1, s17, s1
	v_add3_u32 v21, v21, v22, s67
	s_add_i32 s1, s1, 2
	ds_write_b16_d16_hi v16, v21 offset:10240
	v_cvt_f32_i32_e32 v21, s1
	v_sub_f32_e32 v2, v0, v2
	ds_read_u16 v0, v16 offset:2560
	s_or_b32 s1, s0, 20
	v_rcp_iflag_f32_e32 v21, v21
	s_max_i32 s16, s16, 2
	s_min_i32 s17, s1, s25
	s_waitcnt lgkmcnt(0)
	v_lshlrev_b32_e32 v0, 16, v0
	v_add_f32_e32 v2, v2, v0
	v_fma_f32 v21, v21, v2, -v5
	v_bfe_u32 v22, v21, 16, 1
	s_sub_i32 s16, s17, s16
	v_add3_u32 v21, v21, v22, s67
	s_add_i32 s16, s16, 2
	ds_write_b16_d16_hi v16, v21 offset:10368
	v_cvt_f32_i32_e32 v21, s16
	v_sub_f32_e32 v2, v2, v1
	ds_read_u16 v1, v16 offset:2688
	s_max_i32 s16, s13, 2
	v_rcp_iflag_f32_e32 v21, v21
	s_or_b32 s13, s0, 21
	s_min_i32 s17, s13, s25
	s_waitcnt lgkmcnt(0)
	v_lshlrev_b32_e32 v1, 16, v1
	v_add_f32_e32 v2, v2, v1
	v_fma_f32 v21, v21, v2, -v0
	v_bfe_u32 v22, v21, 16, 1
	s_sub_i32 s16, s17, s16
	v_add3_u32 v21, v21, v22, s67
	s_add_i32 s16, s16, 2
	ds_write_b16_d16_hi v16, v21 offset:10496
	v_cvt_f32_i32_e32 v21, s16
	v_sub_f32_e32 v2, v2, v3
	ds_read_u16 v3, v16 offset:2816
	s_or_b32 s16, s0, 22
	v_rcp_iflag_f32_e32 v21, v21
	s_max_i32 s1, s1, 2
	s_min_i32 s17, s16, s25
	s_waitcnt lgkmcnt(0)
	v_lshlrev_b32_e32 v3, 16, v3
	v_add_f32_e32 v2, v2, v3
	v_fma_f32 v21, v21, v2, -v1
	v_bfe_u32 v22, v21, 16, 1
	s_sub_i32 s1, s17, s1
	v_add3_u32 v21, v21, v22, s67
	s_add_i32 s1, s1, 2
	ds_write_b16_d16_hi v16, v21 offset:10624
	v_cvt_f32_i32_e32 v21, s1
	v_sub_f32_e32 v2, v2, v5
	ds_read_u16 v5, v16 offset:2944
	s_max_i32 s1, s13, 2
	v_rcp_iflag_f32_e32 v21, v21
	s_or_b32 s13, s0, 23
	s_min_i32 s17, s13, s25
	s_waitcnt lgkmcnt(0)
	v_lshlrev_b32_e32 v5, 16, v5
	v_add_f32_e32 v2, v2, v5
	v_fma_f32 v21, v21, v2, -v3
	v_bfe_u32 v22, v21, 16, 1
	s_sub_i32 s1, s17, s1
	v_add3_u32 v21, v21, v22, s67
	s_add_i32 s1, s1, 2
	ds_write_b16_d16_hi v16, v21 offset:10752
	v_cvt_f32_i32_e32 v21, s1
	v_sub_f32_e32 v0, v2, v0
	ds_read_u16 v2, v16 offset:3072
	s_max_i32 s1, s16, 2
	v_rcp_iflag_f32_e32 v21, v21
	s_or_b32 s16, s0, 24
	s_min_i32 s17, s16, s25
	s_waitcnt lgkmcnt(0)
	v_lshlrev_b32_e32 v2, 16, v2
	v_add_f32_e32 v0, v0, v2
	v_fma_f32 v21, v21, v0, -v5
	v_bfe_u32 v22, v21, 16, 1
	s_sub_i32 s1, s17, s1
	v_add3_u32 v21, v21, v22, s67
	s_add_i32 s1, s1, 2
	ds_write_b16_d16_hi v16, v21 offset:10880
	v_cvt_f32_i32_e32 v21, s1
	v_sub_f32_e32 v0, v0, v1
	ds_read_u16 v1, v16 offset:3200
	s_max_i32 s1, s13, 2
	v_rcp_iflag_f32_e32 v21, v21
	s_or_b32 s13, s0, 25
	s_min_i32 s17, s13, s25
	s_waitcnt lgkmcnt(0)
	v_lshlrev_b32_e32 v1, 16, v1
	v_add_f32_e32 v0, v0, v1
	v_fma_f32 v21, v21, v0, -v2
	v_bfe_u32 v22, v21, 16, 1
	s_sub_i32 s1, s17, s1
	v_add3_u32 v21, v21, v22, s67
	s_add_i32 s1, s1, 2
	ds_write_b16_d16_hi v16, v21 offset:11008
	v_cvt_f32_i32_e32 v21, s1
	v_sub_f32_e32 v0, v0, v3
	ds_read_u16 v3, v16 offset:3328
	s_max_i32 s1, s16, 2
	v_rcp_iflag_f32_e32 v21, v21
	s_or_b32 s16, s0, 26
	s_min_i32 s17, s16, s25
	s_waitcnt lgkmcnt(0)
	v_lshlrev_b32_e32 v3, 16, v3
	v_add_f32_e32 v0, v0, v3
	v_fma_f32 v21, v21, v0, -v1
	v_bfe_u32 v22, v21, 16, 1
	s_sub_i32 s1, s17, s1
	v_add3_u32 v21, v21, v22, s67
	s_add_i32 s1, s1, 2
	ds_write_b16_d16_hi v16, v21 offset:11136
	v_cvt_f32_i32_e32 v21, s1
	v_sub_f32_e32 v0, v0, v5
	ds_read_u16 v5, v16 offset:3456
	s_max_i32 s1, s13, 2
	v_rcp_iflag_f32_e32 v21, v21
	s_or_b32 s13, s0, 27
	s_min_i32 s17, s13, s25
	s_waitcnt lgkmcnt(0)
	v_lshlrev_b32_e32 v5, 16, v5
	v_add_f32_e32 v0, v0, v5
	v_fma_f32 v21, v21, v0, -v3
	v_bfe_u32 v22, v21, 16, 1
	s_sub_i32 s1, s17, s1
	v_add3_u32 v21, v21, v22, s67
	s_add_i32 s1, s1, 2
	ds_write_b16_d16_hi v16, v21 offset:11264
	v_cvt_f32_i32_e32 v21, s1
	v_sub_f32_e32 v2, v0, v2
	ds_read_u16 v0, v16 offset:3584
	s_or_b32 s1, s0, 28
	v_rcp_iflag_f32_e32 v21, v21
	s_max_i32 s16, s16, 2
	s_min_i32 s17, s1, s25
	s_waitcnt lgkmcnt(0)
	v_lshlrev_b32_e32 v0, 16, v0
	v_add_f32_e32 v2, v2, v0
	v_fma_f32 v21, v21, v2, -v5
	v_bfe_u32 v22, v21, 16, 1
	s_sub_i32 s16, s17, s16
	v_add3_u32 v21, v21, v22, s67
	s_add_i32 s16, s16, 2
	ds_write_b16_d16_hi v16, v21 offset:11392
	v_cvt_f32_i32_e32 v21, s16
	v_sub_f32_e32 v2, v2, v1
	ds_read_u16 v1, v16 offset:3712
	s_max_i32 s16, s13, 2
	v_rcp_iflag_f32_e32 v21, v21
	s_or_b32 s13, s0, 29
	s_min_i32 s17, s13, s25
	s_waitcnt lgkmcnt(0)
	v_lshlrev_b32_e32 v1, 16, v1
	v_add_f32_e32 v2, v2, v1
	v_fma_f32 v21, v21, v2, -v0
	v_bfe_u32 v22, v21, 16, 1
	s_sub_i32 s16, s17, s16
	v_add3_u32 v21, v21, v22, s67
	s_add_i32 s16, s16, 2
	ds_write_b16_d16_hi v16, v21 offset:11520
	v_cvt_f32_i32_e32 v21, s16
	v_sub_f32_e32 v2, v2, v3
	ds_read_u16 v3, v16 offset:3840
	s_or_b32 s16, s0, 30
	v_rcp_iflag_f32_e32 v21, v21
	s_max_i32 s1, s1, 2
	s_min_i32 s17, s16, s25
	s_waitcnt lgkmcnt(0)
	v_lshlrev_b32_e32 v3, 16, v3
	v_add_f32_e32 v2, v2, v3
	v_fma_f32 v21, v21, v2, -v1
	v_bfe_u32 v22, v21, 16, 1
	s_sub_i32 s1, s17, s1
	v_add3_u32 v21, v21, v22, s67
	s_add_i32 s1, s1, 2
	ds_write_b16_d16_hi v16, v21 offset:11648
	v_cvt_f32_i32_e32 v21, s1
	v_sub_f32_e32 v2, v2, v5
	ds_read_u16 v5, v16 offset:3968
	s_max_i32 s1, s13, 2
	v_rcp_iflag_f32_e32 v21, v21
	s_or_b32 s13, s0, 31
	s_min_i32 s17, s13, s25
	s_waitcnt lgkmcnt(0)
	v_lshlrev_b32_e32 v5, 16, v5
	v_add_f32_e32 v2, v2, v5
	v_fma_f32 v21, v21, v2, -v3
	v_bfe_u32 v22, v21, 16, 1
	s_sub_i32 s1, s17, s1
	v_add3_u32 v21, v21, v22, s67
	s_add_i32 s1, s1, 2
	ds_write_b16_d16_hi v16, v21 offset:11776
	v_cvt_f32_i32_e32 v21, s1
	v_sub_f32_e32 v0, v2, v0
	ds_read_u16 v2, v16 offset:4096
	s_max_i32 s1, s16, 2
	v_rcp_iflag_f32_e32 v21, v21
	s_add_i32 s16, s0, 32
	s_min_i32 s16, s16, s25
	s_waitcnt lgkmcnt(0)
	v_lshlrev_b32_e32 v2, 16, v2
	v_add_f32_e32 v0, v0, v2
	v_fma_f32 v5, v21, v0, -v5
	v_bfe_u32 v21, v5, 16, 1
	s_sub_i32 s1, s16, s1
	v_add3_u32 v5, v5, v21, s67
	s_add_i32 s1, s1, 2
	ds_write_b16_d16_hi v16, v5 offset:11904
	v_cvt_f32_i32_e32 v5, s1
	v_sub_f32_e32 v0, v0, v1
	ds_read_u16 v1, v16 offset:4224
	s_add_i32 s0, s0, 33
	v_rcp_iflag_f32_e32 v5, v5
	s_max_i32 s1, s13, 2
	s_min_i32 s0, s0, s25
	s_waitcnt lgkmcnt(0)
	v_lshlrev_b32_e32 v1, 16, v1
	v_add_f32_e32 v0, v0, v1
	v_fma_f32 v2, v5, v0, -v2
	v_bfe_u32 v5, v2, 16, 1
	v_add3_u32 v2, v2, v5, s67
	ds_write_b16_d16_hi v16, v2 offset:12032
	ds_read_u16 v2, v16 offset:4352
	s_sub_i32 s0, s0, s1
	v_sub_f32_e32 v0, v0, v3
	s_add_i32 s0, s0, 2
	v_or_b32_e32 v22, s24, v99
	s_waitcnt lgkmcnt(0)
	v_lshlrev_b32_e32 v2, 16, v2
	v_add_f32_e32 v0, v0, v2
	v_cvt_f32_i32_e32 v2, s0
	v_ashrrev_i32_e32 v23, 31, v22
	v_lshlrev_b64 v[22:23], 11, v[22:23]
	v_lshl_add_u64 v[22:23], v[8:9], 0, v[22:23]
	v_rcp_iflag_f32_e32 v2, v2
	s_nop 0
	v_fma_f32 v0, v2, v0, -v1
	v_bfe_u32 v1, v0, 16, 1
	v_add3_u32 v0, v0, v1, s67
	ds_write_b16_d16_hi v16, v0 offset:12160
	s_waitcnt lgkmcnt(0)
	ds_read_b128 v[0:3], v18 offset:8192
	v_or_b32_e32 v18, s24, v118
	s_waitcnt lgkmcnt(0)
	global_store_dwordx4 v[22:23], v[0:3], off
	ds_read_b128 v[0:3], v19 offset:8192
	v_ashrrev_i32_e32 v19, 31, v18
	v_lshlrev_b64 v[18:19], 11, v[18:19]
	v_lshl_add_u64 v[18:19], v[8:9], 0, v[18:19]
	s_waitcnt lgkmcnt(0)
	global_store_dwordx4 v[18:19], v[0:3], off
	ds_read_b128 v[0:3], v20 offset:8192
	v_or_b32_e32 v18, s24, v119
	v_ashrrev_i32_e32 v19, 31, v18
	v_lshlrev_b64 v[18:19], 11, v[18:19]
	v_lshl_add_u64 v[18:19], v[8:9], 0, v[18:19]
	s_waitcnt lgkmcnt(0)
	global_store_dwordx4 v[18:19], v[0:3], off
	ds_read_b128 v[0:3], v4 offset:8192
	v_or_b32_e32 v4, s24, v120
	v_ashrrev_i32_e32 v5, 31, v4
	v_lshlrev_b64 v[4:5], 11, v[4:5]
	v_lshl_add_u64 v[4:5], v[8:9], 0, v[4:5]
	s_waitcnt lgkmcnt(0)
	global_store_dwordx4 v[4:5], v[0:3], off
	s_waitcnt lgkmcnt(0)

.LBB0_528:
	s_or_b64 exec, exec, s[0:1]
	v_add_u32_e32 v5, s6, v121
	v_cmp_le_i32_e32 vcc, s26, v5
	v_cmp_gt_i32_e64 s[0:1], s27, v5
	s_and_b64 s[4:5], vcc, s[0:1]
	v_mov_b32_e32 v0, 0
	v_mov_b32_e32 v1, 0
	v_mov_b32_e32 v2, 0
	v_mov_b32_e32 v3, 0
	v_mov_b32_e32 v242, 0
	v_mov_b32_e32 v243, 0
	v_mov_b32_e32 v244, 0
	v_mov_b32_e32 v245, 0
	s_and_saveexec_b64 s[0:1], s[4:5]
	s_cbranch_execz .LBB0_530
	v_mad_i64_i32 v[242:243], s[4:5], v5, s53, v[6:7]
	global_load_dwordx4 v[242:245], v[242:243], off
.LBB0_530:
	s_or_b64 exec, exec, s[0:1]
	s_and_saveexec_b64 s[4:5], s[40:41]
	s_cbranch_execz .LBB0_534
	v_add_u32_e32 v5, s6, v122
	v_cmp_le_i32_e32 vcc, s26, v5
	v_cmp_gt_i32_e64 s[0:1], s27, v5
	s_and_b64 s[6:7], vcc, s[0:1]
	v_mov_b32_e32 v0, 0
	v_mov_b32_e32 v1, 0
	v_mov_b32_e32 v2, 0
	v_mov_b32_e32 v3, 0
	s_and_saveexec_b64 s[0:1], s[6:7]
	s_cbranch_execz .LBB0_533
	v_mad_i64_i32 v[0:1], s[6:7], v5, s53, v[6:7]
	global_load_dwordx4 v[0:3], v[0:1], off

.LBB0_534:
	s_or_b64 exec, exec, s[4:5]
	s_waitcnt vmcnt(0)
	v_add_u32_e32 v18, v10, v11
	ds_write_b128 v18, v[226:229]
	v_add_u32_e32 v19, v10, v12
	ds_write_b128 v19, v[230:233]
	v_add_u32_e32 v20, v10, v13
	ds_write_b128 v20, v[234:237]
	v_add_u32_e32 v4, v10, v14
	ds_write_b128 v4, v[238:241]
	v_add_u32_e32 v5, v10, v15
	ds_write_b128 v5, v[242:245]
	s_waitcnt lgkmcnt(0)
	ds_read_u16 v0, v16
	ds_read_u16 v2, v16 offset:128
	ds_read_u16 v3, v16 offset:1152
	s_sub_i32 s0, s24, s26
	s_or_b32 s6, s0, 8
	s_waitcnt lgkmcnt(2)
	v_lshlrev_b32_e32 v0, 16, v0
	v_add_f32_e32 v1, 0, v0
	s_waitcnt lgkmcnt(1)
	v_lshlrev_b32_e32 v2, 16, v2
	v_add_f32_e32 v1, v1, v2
	ds_read_u16 v2, v16 offset:256
	ds_read_u16 v5, v16 offset:1280
	s_waitcnt lgkmcnt(2)
	v_lshlrev_b32_e32 v3, 16, v3
	s_max_i32 s1, s0, 8
	ds_read_u16 v21, v16 offset:1408
	s_waitcnt lgkmcnt(2)
	v_lshlrev_b32_e32 v2, 16, v2
	v_add_f32_e32 v1, v1, v2
	ds_read_u16 v2, v16 offset:384
	s_waitcnt lgkmcnt(2)
	v_lshlrev_b32_e32 v5, 16, v5
	s_waitcnt lgkmcnt(1)
	v_lshlrev_b32_e32 v21, 16, v21
	ds_read_u16 v24, v16 offset:1792
	s_min_i32 s4, s6, s25
	s_waitcnt lgkmcnt(1)
	v_lshlrev_b32_e32 v2, 16, v2
	v_add_f32_e32 v1, v1, v2
	ds_read_u16 v2, v16 offset:512
	s_sub_i32 s1, s4, s1
	s_add_i32 s1, s1, 8
	s_or_b32 s5, s0, 9
	s_min_i32 s4, s5, s25
	s_waitcnt lgkmcnt(0)
	v_lshlrev_b32_e32 v2, 16, v2
	v_add_f32_e32 v1, v1, v2
	ds_read_u16 v2, v16 offset:640
	s_or_b32 s7, s0, 10
	s_or_b32 s13, s0, 11
	s_or_b32 s16, s0, 12
	s_or_b32 s17, s0, 13
	s_waitcnt lgkmcnt(0)
	v_lshlrev_b32_e32 v2, 16, v2
	v_add_f32_e32 v1, v1, v2
	ds_read_u16 v2, v16 offset:768
	v_lshlrev_b32_e32 v24, 16, v24
	s_max_i32 s6, s6, 8
	s_max_i32 s5, s5, 8
	ds_read_u16 v23, v16 offset:1664
	s_waitcnt lgkmcnt(1)
	v_lshlrev_b32_e32 v2, 16, v2
	v_add_f32_e32 v1, v1, v2
	ds_read_u16 v2, v16 offset:896
	s_waitcnt lgkmcnt(1)
	v_lshlrev_b32_e32 v23, 16, v23
	s_waitcnt lgkmcnt(0)
	v_lshlrev_b32_e32 v2, 16, v2
	v_add_f32_e32 v1, v1, v2
	ds_read_u16 v2, v16 offset:1024
	s_waitcnt lgkmcnt(0)
	v_lshlrev_b32_e32 v2, 16, v2
	v_add_f32_e32 v1, v1, v2
	v_add_f32_e32 v1, v1, v3
	v_add_f32_e32 v1, v1, v5
	v_add_f32_e32 v1, v1, v21
	ds_read_u16 v21, v16 offset:1536
	s_waitcnt lgkmcnt(0)
	v_lshlrev_b32_e32 v21, 16, v21
	v_add_f32_e32 v1, v1, v21
	ds_read_u16 v21, v16 offset:1664
	s_waitcnt lgkmcnt(0)
	v_lshlrev_b32_e32 v21, 16, v21
	v_add_f32_e32 v1, v1, v21
	ds_read_u16 v21, v16 offset:1792
	s_waitcnt lgkmcnt(0)
	v_lshlrev_b32_e32 v21, 16, v21
	v_add_f32_e32 v1, v1, v21
	ds_read_u16 v21, v16 offset:1920
	s_waitcnt lgkmcnt(0)
	v_lshlrev_b32_e32 v22, 16, v21
	v_cvt_f32_i32_e32 v21, s1
	v_add_f32_e32 v1, v1, v22
	s_or_b32 s1, s0, 1
	s_max_i32 s1, s1, 8
	v_rcp_iflag_f32_e32 v21, v21
	s_sub_i32 s1, s4, s1
	s_add_i32 s1, s1, 8
	v_sub_f32_e32 v0, v1, v0
	v_fma_f32 v2, v21, v1, -v2
	v_bfe_u32 v21, v2, 16, 1
	v_add3_u32 v2, v2, v21, s67
	ds_write_b16_d16_hi v16, v2 offset:8192
	v_cvt_f32_i32_e32 v2, s1
	ds_read_u16 v1, v16 offset:2048
	s_or_b32 s1, s0, 2
	s_max_i32 s1, s1, 8
	v_rcp_iflag_f32_e32 v2, v2
	s_min_i32 s4, s7, s25
	s_waitcnt lgkmcnt(0)
	v_lshlrev_b32_e32 v1, 16, v1
	v_add_f32_e32 v0, v0, v1
	v_fma_f32 v2, v2, v0, -v3
	v_bfe_u32 v3, v2, 16, 1
	v_add3_u32 v2, v2, v3, s67
	ds_write_b16_d16_hi v16, v2 offset:8320
	ds_read_u16 v2, v16 offset:128
	ds_read_u16 v21, v16 offset:1408
	s_sub_i32 s1, s4, s1
	s_add_i32 s1, s1, 8
	v_cvt_f32_i32_e32 v3, s1
	s_waitcnt lgkmcnt(1)
	v_lshlrev_b32_e32 v2, 16, v2
	v_sub_f32_e32 v0, v0, v2
	ds_read_u16 v2, v16 offset:2176
	v_rcp_iflag_f32_e32 v3, v3
	s_or_b32 s1, s0, 3
	s_max_i32 s1, s1, 8
	s_min_i32 s4, s13, s25
	s_waitcnt lgkmcnt(0)
	v_lshlrev_b32_e32 v2, 16, v2
	v_add_f32_e32 v0, v0, v2
	v_fma_f32 v3, v3, v0, -v5
	v_bfe_u32 v5, v3, 16, 1
	v_add3_u32 v3, v3, v5, s67
	ds_write_b16_d16_hi v16, v3 offset:8448
	ds_read_u16 v3, v16 offset:256
	s_sub_i32 s1, s4, s1
	s_add_i32 s1, s1, 8
	v_cvt_f32_i32_e32 v5, s1
	v_lshlrev_b32_e32 v21, 16, v21
	s_waitcnt lgkmcnt(0)
	v_lshlrev_b32_e32 v3, 16, v3
	v_sub_f32_e32 v0, v0, v3
	ds_read_u16 v3, v16 offset:2304
	v_rcp_iflag_f32_e32 v5, v5
	s_or_b32 s1, s0, 4
	s_max_i32 s1, s1, 8
	s_min_i32 s4, s16, s25
	s_waitcnt lgkmcnt(0)
	v_lshlrev_b32_e32 v3, 16, v3
	v_add_f32_e32 v0, v0, v3
	v_fma_f32 v5, v5, v0, -v21
	v_bfe_u32 v21, v5, 16, 1
	v_add3_u32 v5, v5, v21, s67
	ds_write_b16_d16_hi v16, v5 offset:8576
	ds_read_u16 v5, v16 offset:384
	ds_read_u16 v21, v16 offset:1536
	s_sub_i32 s1, s4, s1
	s_add_i32 s1, s1, 8
	s_min_i32 s4, s17, s25
	s_waitcnt lgkmcnt(1)
	v_lshlrev_b32_e32 v5, 16, v5
	v_sub_f32_e32 v0, v0, v5
	ds_read_u16 v5, v16 offset:2432
	s_waitcnt lgkmcnt(1)
	v_lshlrev_b32_e32 v21, 16, v21
	s_waitcnt lgkmcnt(0)
	v_lshlrev_b32_e32 v25, 16, v5
	v_cvt_f32_i32_e32 v5, s1
	v_add_f32_e32 v0, v0, v25
	s_or_b32 s1, s0, 5
	s_max_i32 s1, s1, 8
	v_rcp_iflag_f32_e32 v5, v5
	s_sub_i32 s1, s4, s1
	s_add_i32 s1, s1, 8
	v_fma_f32 v5, v5, v0, -v21
	v_bfe_u32 v21, v5, 16, 1
	v_add3_u32 v5, v5, v21, s67
	ds_write_b16_d16_hi v16, v5 offset:8704
	ds_read_u16 v5, v16 offset:512
	v_cvt_f32_i32_e32 v21, s1
	s_or_b32 s1, s0, 6
	s_max_i32 s4, s1, 8
	s_or_b32 s1, s0, 14
	s_waitcnt lgkmcnt(0)
	v_lshlrev_b32_e32 v5, 16, v5
	v_sub_f32_e32 v0, v0, v5
	ds_read_u16 v5, v16 offset:2560
	v_rcp_iflag_f32_e32 v21, v21
	s_min_i32 s28, s1, s25
	s_sub_i32 s4, s28, s4
	s_add_i32 s4, s4, 8
	s_waitcnt lgkmcnt(0)
	v_lshlrev_b32_e32 v5, 16, v5
	v_add_f32_e32 v0, v0, v5
	v_fma_f32 v21, v21, v0, -v23
	v_bfe_u32 v23, v21, 16, 1
	v_add3_u32 v21, v21, v23, s67
	ds_write_b16_d16_hi v16, v21 offset:8832
	ds_read_u16 v21, v16 offset:640
	v_cvt_f32_i32_e32 v23, s4
	s_or_b32 s4, s0, 7
	s_max_i32 s28, s4, 8
	s_or_b32 s4, s0, 15
	s_waitcnt lgkmcnt(0)
	v_lshlrev_b32_e32 v21, 16, v21
	v_sub_f32_e32 v0, v0, v21
	ds_read_u16 v21, v16 offset:2688
	v_rcp_iflag_f32_e32 v23, v23
	s_min_i32 s29, s4, s25
	s_sub_i32 s28, s29, s28
	s_add_i32 s28, s28, 8
	s_waitcnt lgkmcnt(0)
	v_lshlrev_b32_e32 v21, 16, v21
	v_add_f32_e32 v0, v0, v21
	v_fma_f32 v23, v23, v0, -v24
	v_bfe_u32 v24, v23, 16, 1
	v_add3_u32 v23, v23, v24, s67
	ds_write_b16_d16_hi v16, v23 offset:8960
	ds_read_u16 v23, v16 offset:768
	v_cvt_f32_i32_e32 v24, s28
	s_or_b32 s28, s0, 16
	s_min_i32 s29, s28, s25
	s_sub_i32 s6, s29, s6
	s_waitcnt lgkmcnt(0)
	v_lshlrev_b32_e32 v23, 16, v23
	v_sub_f32_e32 v23, v0, v23
	ds_read_u16 v0, v16 offset:2816
	v_rcp_iflag_f32_e32 v24, v24
	s_add_i32 s6, s6, 8
	s_or_b32 s29, s0, 17
	s_max_i32 s4, s4, 8
	s_waitcnt lgkmcnt(0)
	v_lshlrev_b32_e32 v0, 16, v0
	v_add_f32_e32 v23, v23, v0
	v_fma_f32 v22, v24, v23, -v22
	v_bfe_u32 v24, v22, 16, 1
	v_add3_u32 v22, v22, v24, s67
	ds_write_b16_d16_hi v16, v22 offset:9088
	ds_read_u16 v22, v16 offset:896
	v_cvt_f32_i32_e32 v24, s6
	s_min_i32 s6, s29, s25
	s_sub_i32 s5, s6, s5
	s_add_i32 s5, s5, 8
	s_waitcnt lgkmcnt(0)
	v_lshlrev_b32_e32 v22, 16, v22
	v_sub_f32_e32 v23, v23, v22
	ds_read_u16 v22, v16 offset:2944
	v_rcp_iflag_f32_e32 v24, v24
	s_max_i32 s6, s7, 8
	s_waitcnt lgkmcnt(0)
	v_lshlrev_b32_e32 v22, 16, v22
	v_add_f32_e32 v23, v23, v22
	v_fma_f32 v1, v24, v23, -v1
	v_bfe_u32 v24, v1, 16, 1
	v_add3_u32 v1, v1, v24, s67
	ds_write_b16_d16_hi v16, v1 offset:9216
	ds_read_u16 v1, v16 offset:1024
	v_cvt_f32_i32_e32 v24, s5
	s_or_b32 s5, s0, 18
	s_min_i32 s7, s5, s25
	s_sub_i32 s6, s7, s6
	s_waitcnt lgkmcnt(0)
	v_lshlrev_b32_e32 v1, 16, v1
	v_sub_f32_e32 v1, v23, v1
	ds_read_u16 v23, v16 offset:3072
	v_rcp_iflag_f32_e32 v24, v24
	s_add_i32 s6, s6, 8
	s_max_i32 s7, s13, 8
	s_max_i32 s5, s5, 8
	s_waitcnt lgkmcnt(0)
	v_lshlrev_b32_e32 v23, 16, v23
	v_add_f32_e32 v1, v1, v23
	v_fma_f32 v2, v24, v1, -v2
	v_bfe_u32 v24, v2, 16, 1
	v_add3_u32 v2, v2, v24, s67
	ds_write_b16_d16_hi v16, v2 offset:9344
	ds_read_u16 v2, v16 offset:1152
	s_waitcnt lgkmcnt(0)
	v_lshlrev_b32_e32 v2, 16, v2
	v_sub_f32_e32 v1, v1, v2
	ds_read_u16 v2, v16 offset:3200
	s_waitcnt lgkmcnt(0)
	v_lshlrev_b32_e32 v24, 16, v2
	v_cvt_f32_i32_e32 v2, s6
	v_add_f32_e32 v1, v1, v24
	s_or_b32 s6, s0, 19
	s_min_i32 s13, s6, s25
	v_rcp_iflag_f32_e32 v2, v2
	s_sub_i32 s7, s13, s7
	s_add_i32 s7, s7, 8
	s_max_i32 s13, s16, 8
	v_fma_f32 v2, v2, v1, -v3
	v_bfe_u32 v3, v2, 16, 1
	v_add3_u32 v2, v2, v3, s67
	ds_write_b16_d16_hi v16, v2 offset:9472
	ds_read_u16 v2, v16 offset:1280
	v_cvt_f32_i32_e32 v3, s7
	s_or_b32 s7, s0, 20
	s_min_i32 s16, s7, s25
	s_sub_i32 s13, s16, s13
	s_waitcnt lgkmcnt(0)
	v_lshlrev_b32_e32 v2, 16, v2
	v_sub_f32_e32 v2, v1, v2
	ds_read_u16 v1, v16 offset:3328
	v_rcp_iflag_f32_e32 v3, v3
	s_add_i32 s13, s13, 8
	s_max_i32 s16, s17, 8
	s_max_i32 s6, s6, 8
	s_waitcnt lgkmcnt(0)
	v_lshlrev_b32_e32 v1, 16, v1
	v_add_f32_e32 v2, v2, v1
	v_fma_f32 v3, v3, v2, -v25
	v_bfe_u32 v25, v3, 16, 1
	v_add3_u32 v3, v3, v25, s67
	ds_write_b16_d16_hi v16, v3 offset:9600
	ds_read_u16 v3, v16 offset:1408
	v_cvt_f32_i32_e32 v25, s13
	s_or_b32 s13, s0, 21
	s_min_i32 s17, s13, s25
	s_sub_i32 s16, s17, s16
	s_waitcnt lgkmcnt(0)
	v_lshlrev_b32_e32 v3, 16, v3
	v_sub_f32_e32 v3, v2, v3
	ds_read_u16 v2, v16 offset:3456
	v_rcp_iflag_f32_e32 v25, v25
	s_add_i32 s16, s16, 8
	s_max_i32 s7, s7, 8
	s_max_i32 s13, s13, 8
	s_waitcnt lgkmcnt(0)
	v_lshlrev_b32_e32 v2, 16, v2
	v_add_f32_e32 v3, v3, v2
	v_fma_f32 v5, v25, v3, -v5
	v_bfe_u32 v25, v5, 16, 1
	v_add3_u32 v5, v5, v25, s67
	ds_write_b16_d16_hi v16, v5 offset:9728
	ds_read_u16 v5, v16 offset:1536
	v_cvt_f32_i32_e32 v25, s16
	s_max_i32 s16, s1, 8
	s_or_b32 s1, s0, 22
	s_min_i32 s17, s1, s25
	s_waitcnt lgkmcnt(0)
	v_lshlrev_b32_e32 v5, 16, v5
	v_sub_f32_e32 v5, v3, v5
	ds_read_u16 v3, v16 offset:3584
	v_rcp_iflag_f32_e32 v25, v25
	s_sub_i32 s16, s17, s16
	s_add_i32 s16, s16, 8
	s_max_i32 s1, s1, 8
	s_waitcnt lgkmcnt(0)
	v_lshlrev_b32_e32 v3, 16, v3
	v_add_f32_e32 v5, v5, v3
	v_fma_f32 v21, v25, v5, -v21
	v_bfe_u32 v25, v21, 16, 1
	v_add3_u32 v21, v21, v25, s67
	ds_write_b16_d16_hi v16, v21 offset:9856
	ds_read_u16 v21, v16 offset:1664
	s_waitcnt lgkmcnt(0)
	v_lshlrev_b32_e32 v21, 16, v21
	v_sub_f32_e32 v5, v5, v21
	ds_read_u16 v21, v16 offset:3712
	s_waitcnt lgkmcnt(0)
	v_lshlrev_b32_e32 v25, 16, v21
	v_cvt_f32_i32_e32 v21, s16
	v_add_f32_e32 v5, v5, v25
	s_or_b32 s16, s0, 23
	s_min_i32 s17, s16, s25
	v_rcp_iflag_f32_e32 v21, v21
	s_sub_i32 s4, s17, s4
	s_add_i32 s4, s4, 8
	s_or_b32 s17, s0, 24
	v_fma_f32 v0, v21, v5, -v0
	v_bfe_u32 v21, v0, 16, 1
	v_add3_u32 v0, v0, v21, s67
	ds_write_b16_d16_hi v16, v0 offset:9984
	ds_read_u16 v0, v16 offset:1792
	v_cvt_f32_i32_e32 v21, s4
	s_max_i32 s4, s28, 8
	s_min_i32 s28, s17, s25
	s_sub_i32 s4, s28, s4
	s_waitcnt lgkmcnt(0)
	v_lshlrev_b32_e32 v0, 16, v0
	v_sub_f32_e32 v5, v5, v0
	ds_read_u16 v0, v16 offset:3840
	v_rcp_iflag_f32_e32 v21, v21
	s_add_i32 s4, s4, 8
	s_or_b32 s28, s0, 25
	s_max_i32 s16, s16, 8
	s_waitcnt lgkmcnt(0)
	v_lshlrev_b32_e32 v0, 16, v0
	v_add_f32_e32 v5, v5, v0
	v_fma_f32 v21, v21, v5, -v22
	v_bfe_u32 v22, v21, 16, 1
	v_add3_u32 v21, v21, v22, s67
	ds_write_b16_d16_hi v16, v21 offset:10112
	ds_read_u16 v21, v16 offset:1920
	v_cvt_f32_i32_e32 v22, s4
	s_max_i32 s4, s29, 8
	s_min_i32 s29, s28, s25
	s_sub_i32 s4, s29, s4
	s_waitcnt lgkmcnt(0)
	v_lshlrev_b32_e32 v21, 16, v21
	v_sub_f32_e32 v5, v5, v21
	ds_read_u16 v21, v16 offset:3968
	v_rcp_iflag_f32_e32 v22, v22
	s_add_i32 s4, s4, 8
	s_waitcnt lgkmcnt(0)
	v_lshlrev_b32_e32 v21, 16, v21
	v_add_f32_e32 v5, v5, v21
	v_fma_f32 v22, v22, v5, -v23
	v_bfe_u32 v23, v22, 16, 1
	v_add3_u32 v22, v22, v23, s67
	ds_write_b16_d16_hi v16, v22 offset:10240
	ds_read_u16 v22, v16 offset:2048
	v_cvt_f32_i32_e32 v23, s4
	s_or_b32 s4, s0, 26
	s_min_i32 s29, s4, s25
	s_sub_i32 s5, s29, s5
	s_waitcnt lgkmcnt(0)
	v_lshlrev_b32_e32 v22, 16, v22
	v_sub_f32_e32 v5, v5, v22
	ds_read_u16 v22, v16 offset:4096
	v_rcp_iflag_f32_e32 v23, v23
	s_add_i32 s5, s5, 8
	s_max_i32 s4, s4, 8
	s_waitcnt lgkmcnt(0)
	v_lshlrev_b32_e32 v22, 16, v22
	v_add_f32_e32 v5, v5, v22
	v_fma_f32 v23, v23, v5, -v24
	v_bfe_u32 v24, v23, 16, 1
	v_add3_u32 v23, v23, v24, s67
	ds_write_b16_d16_hi v16, v23 offset:10368
	ds_read_u16 v23, v16 offset:2176
	s_waitcnt lgkmcnt(0)
	v_lshlrev_b32_e32 v23, 16, v23
	v_sub_f32_e32 v5, v5, v23
	ds_read_u16 v23, v16 offset:4224
	s_waitcnt lgkmcnt(0)
	v_lshlrev_b32_e32 v24, 16, v23
	v_cvt_f32_i32_e32 v23, s5
	v_add_f32_e32 v5, v5, v24
	s_or_b32 s5, s0, 27
	s_min_i32 s29, s5, s25
	v_rcp_iflag_f32_e32 v23, v23
	s_sub_i32 s6, s29, s6
	s_add_i32 s6, s6, 8
	v_fma_f32 v1, v23, v5, -v1
	v_bfe_u32 v23, v1, 16, 1
	v_add3_u32 v1, v1, v23, s67
	ds_write_b16_d16_hi v16, v1 offset:10496
	ds_read_u16 v1, v16 offset:2304
	v_cvt_f32_i32_e32 v23, s6
	s_or_b32 s6, s0, 28
	s_min_i32 s29, s6, s25
	s_sub_i32 s7, s29, s7
	s_waitcnt lgkmcnt(0)
	v_lshlrev_b32_e32 v1, 16, v1
	v_sub_f32_e32 v5, v5, v1
	ds_read_u16 v1, v16 offset:4352
	v_rcp_iflag_f32_e32 v23, v23
	s_add_i32 s7, s7, 8
	s_waitcnt lgkmcnt(0)
	v_lshlrev_b32_e32 v1, 16, v1
	v_add_f32_e32 v5, v5, v1
	v_fma_f32 v2, v23, v5, -v2
	v_bfe_u32 v23, v2, 16, 1
	v_add3_u32 v2, v2, v23, s67
	ds_write_b16_d16_hi v16, v2 offset:10624
	ds_read_u16 v2, v16 offset:2432
	v_cvt_f32_i32_e32 v23, s7
	s_or_b32 s7, s0, 29
	s_min_i32 s29, s7, s25
	s_sub_i32 s13, s29, s13
	s_waitcnt lgkmcnt(0)
	v_lshlrev_b32_e32 v2, 16, v2
	v_sub_f32_e32 v5, v5, v2
	ds_read_u16 v2, v16 offset:4480
	v_rcp_iflag_f32_e32 v23, v23
	s_add_i32 s13, s13, 8
	s_waitcnt lgkmcnt(0)
	v_lshlrev_b32_e32 v2, 16, v2
	v_add_f32_e32 v5, v5, v2
	v_fma_f32 v3, v23, v5, -v3
	v_bfe_u32 v23, v3, 16, 1
	v_add3_u32 v3, v3, v23, s67
	ds_write_b16_d16_hi v16, v3 offset:10752
	ds_read_u16 v3, v16 offset:2560
	v_cvt_f32_i32_e32 v23, s13
	s_or_b32 s13, s0, 30
	s_min_i32 s29, s13, s25
	s_sub_i32 s1, s29, s1
	s_waitcnt lgkmcnt(0)
	v_lshlrev_b32_e32 v3, 16, v3
	v_sub_f32_e32 v5, v5, v3
	ds_read_u16 v3, v16 offset:4608
	v_rcp_iflag_f32_e32 v23, v23
	s_add_i32 s1, s1, 8
	s_waitcnt lgkmcnt(0)
	v_lshlrev_b32_e32 v3, 16, v3
	v_add_f32_e32 v5, v5, v3
	v_fma_f32 v23, v23, v5, -v25
	v_bfe_u32 v25, v23, 16, 1
	v_add3_u32 v23, v23, v25, s67
	ds_write_b16_d16_hi v16, v23 offset:10880
	ds_read_u16 v23, v16 offset:2688
	v_cvt_f32_i32_e32 v25, s1
	s_or_b32 s1, s0, 31
	s_min_i32 s29, s1, s25
	s_sub_i32 s16, s29, s16
	s_waitcnt lgkmcnt(0)
	v_lshlrev_b32_e32 v23, 16, v23
	v_sub_f32_e32 v5, v5, v23
	ds_read_u16 v23, v16 offset:4736
	v_rcp_iflag_f32_e32 v25, v25
	s_add_i32 s16, s16, 8
	s_max_i32 s1, s1, 8
	s_waitcnt lgkmcnt(0)
	v_lshlrev_b32_e32 v23, 16, v23
	v_add_f32_e32 v5, v5, v23
	v_fma_f32 v0, v25, v5, -v0
	v_bfe_u32 v25, v0, 16, 1
	v_add3_u32 v0, v0, v25, s67
	ds_write_b16_d16_hi v16, v0 offset:11008
	ds_read_u16 v0, v16 offset:2816
	v_cvt_f32_i32_e32 v25, s16
	s_max_i32 s16, s17, 8
	s_add_i32 s17, s0, 32
	s_min_i32 s17, s17, s25
	s_waitcnt lgkmcnt(0)
	v_lshlrev_b32_e32 v0, 16, v0
	v_sub_f32_e32 v0, v5, v0
	ds_read_u16 v5, v16 offset:4864
	v_rcp_iflag_f32_e32 v25, v25
	s_sub_i32 s16, s17, s16
	s_add_i32 s16, s16, 8
	s_add_i32 s17, s0, 33
	s_waitcnt lgkmcnt(0)
	v_lshlrev_b32_e32 v5, 16, v5
	v_add_f32_e32 v0, v0, v5
	v_fma_f32 v21, v25, v0, -v21
	v_bfe_u32 v25, v21, 16, 1
	v_add3_u32 v21, v21, v25, s67
	ds_write_b16_d16_hi v16, v21 offset:11136
	ds_read_u16 v21, v16 offset:2944
	v_cvt_f32_i32_e32 v25, s16
	s_max_i32 s16, s28, 8
	s_min_i32 s17, s17, s25
	s_sub_i32 s16, s17, s16
	s_waitcnt lgkmcnt(0)
	v_lshlrev_b32_e32 v21, 16, v21
	v_sub_f32_e32 v21, v0, v21
	ds_read_u16 v0, v16 offset:4992
	v_rcp_iflag_f32_e32 v25, v25
	s_add_i32 s16, s16, 8
	s_waitcnt lgkmcnt(0)
	v_lshlrev_b32_e32 v0, 16, v0
	v_add_f32_e32 v21, v21, v0
	v_fma_f32 v22, v25, v21, -v22
	v_bfe_u32 v25, v22, 16, 1
	v_add3_u32 v22, v22, v25, s67
	ds_write_b16_d16_hi v16, v22 offset:11264
	ds_read_u16 v22, v16 offset:3072
	s_waitcnt lgkmcnt(0)
	v_lshlrev_b32_e32 v22, 16, v22
	v_sub_f32_e32 v21, v21, v22
	ds_read_u16 v22, v16 offset:5120
	s_waitcnt lgkmcnt(0)
	v_lshlrev_b32_e32 v22, 16, v22
	v_add_f32_e32 v21, v21, v22
	v_cvt_f32_i32_e32 v22, s16
	s_add_i32 s16, s0, 34
	s_min_i32 s16, s16, s25
	s_sub_i32 s4, s16, s4
	v_rcp_iflag_f32_e32 v22, v22
	s_add_i32 s4, s4, 8
	v_fma_f32 v22, v22, v21, -v24
	v_bfe_u32 v24, v22, 16, 1
	v_add3_u32 v22, v22, v24, s67
	ds_write_b16_d16_hi v16, v22 offset:11392
	ds_read_u16 v22, v16 offset:3200
	s_waitcnt lgkmcnt(0)
	v_lshlrev_b32_e32 v22, 16, v22
	v_sub_f32_e32 v21, v21, v22
	ds_read_u16 v22, v16 offset:5248
	s_waitcnt lgkmcnt(0)
	v_lshlrev_b32_e32 v22, 16, v22
	v_add_f32_e32 v21, v21, v22
	v_cvt_f32_i32_e32 v22, s4
	s_max_i32 s4, s5, 8
	s_add_i32 s5, s0, 35
	s_min_i32 s5, s5, s25
	v_rcp_iflag_f32_e32 v22, v22
	s_sub_i32 s4, s5, s4
	s_add_i32 s4, s4, 8
	s_add_i32 s5, s0, 36
	v_fma_f32 v1, v22, v21, -v1
	v_bfe_u32 v22, v1, 16, 1
	v_add3_u32 v1, v1, v22, s67
	ds_write_b16_d16_hi v16, v1 offset:11520
	ds_read_u16 v1, v16 offset:3328
	s_min_i32 s5, s5, s25
	v_or_b32_e32 v22, s24, v99
	s_waitcnt lgkmcnt(0)
	v_lshlrev_b32_e32 v1, 16, v1
	v_sub_f32_e32 v1, v21, v1
	ds_read_u16 v21, v16 offset:5376
	s_waitcnt lgkmcnt(0)
	v_lshlrev_b32_e32 v21, 16, v21
	v_add_f32_e32 v1, v1, v21
	v_cvt_f32_i32_e32 v21, s4
	s_max_i32 s4, s6, 8
	s_sub_i32 s4, s5, s4
	s_add_i32 s4, s4, 8
	v_rcp_iflag_f32_e32 v21, v21
	s_add_i32 s5, s0, 37
	s_min_i32 s5, s5, s25
	v_fma_f32 v2, v21, v1, -v2
	v_bfe_u32 v21, v2, 16, 1
	v_add3_u32 v2, v2, v21, s67
	ds_write_b16_d16_hi v16, v2 offset:11648
	ds_read_u16 v2, v16 offset:3456
	s_waitcnt lgkmcnt(0)
	v_lshlrev_b32_e32 v2, 16, v2
	v_sub_f32_e32 v1, v1, v2
	ds_read_u16 v2, v16 offset:5504
	s_waitcnt lgkmcnt(0)
	v_lshlrev_b32_e32 v2, 16, v2
	v_add_f32_e32 v1, v1, v2
	v_cvt_f32_i32_e32 v2, s4
	s_max_i32 s4, s7, 8
	s_sub_i32 s4, s5, s4
	s_add_i32 s4, s4, 8
	v_rcp_iflag_f32_e32 v2, v2
	s_add_i32 s5, s0, 38
	s_min_i32 s5, s5, s25
	s_add_i32 s0, s0, 39
	v_fma_f32 v2, v2, v1, -v3
	v_bfe_u32 v3, v2, 16, 1
	v_add3_u32 v2, v2, v3, s67
	ds_write_b16_d16_hi v16, v2 offset:11776
	ds_read_u16 v2, v16 offset:3584
	s_min_i32 s0, s0, s25
	s_sub_i32 s0, s0, s1
	s_add_i32 s0, s0, 8
	s_waitcnt lgkmcnt(0)
	v_lshlrev_b32_e32 v2, 16, v2
	v_sub_f32_e32 v1, v1, v2
	ds_read_u16 v2, v16 offset:5632
	s_waitcnt lgkmcnt(0)
	v_lshlrev_b32_e32 v2, 16, v2
	v_add_f32_e32 v1, v1, v2
	v_cvt_f32_i32_e32 v2, s4
	s_max_i32 s4, s13, 8
	s_sub_i32 s4, s5, s4
	s_add_i32 s4, s4, 8
	v_rcp_iflag_f32_e32 v2, v2
	s_nop 0
	v_fma_f32 v2, v2, v1, -v23
	v_bfe_u32 v3, v2, 16, 1
	v_add3_u32 v2, v2, v3, s67
	ds_write_b16_d16_hi v16, v2 offset:11904
	ds_read_u16 v2, v16 offset:3712
	v_ashrrev_i32_e32 v23, 31, v22
	v_lshlrev_b64 v[22:23], 11, v[22:23]
	v_lshl_add_u64 v[22:23], v[8:9], 0, v[22:23]
	s_waitcnt lgkmcnt(0)
	v_lshlrev_b32_e32 v2, 16, v2
	v_sub_f32_e32 v1, v1, v2
	ds_read_u16 v2, v16 offset:5760
	s_waitcnt lgkmcnt(0)
	v_lshlrev_b32_e32 v2, 16, v2
	v_add_f32_e32 v1, v1, v2
	v_cvt_f32_i32_e32 v2, s4
	v_rcp_iflag_f32_e32 v2, v2
	s_nop 0
	v_fma_f32 v2, v2, v1, -v5
	v_bfe_u32 v3, v2, 16, 1
	v_add3_u32 v2, v2, v3, s67
	ds_write_b16_d16_hi v16, v2 offset:12032
	ds_read_u16 v2, v16 offset:3840
	s_waitcnt lgkmcnt(0)
	v_lshlrev_b32_e32 v2, 16, v2
	v_sub_f32_e32 v1, v1, v2
	ds_read_u16 v2, v16 offset:5888
	s_waitcnt lgkmcnt(0)
	v_lshlrev_b32_e32 v2, 16, v2
	v_add_f32_e32 v1, v1, v2
	v_cvt_f32_i32_e32 v2, s0
	v_rcp_iflag_f32_e32 v2, v2
	s_nop 0
	v_fma_f32 v0, v2, v1, -v0
	v_bfe_u32 v1, v0, 16, 1
	v_add3_u32 v0, v0, v1, s67
	ds_write_b16_d16_hi v16, v0 offset:12160
	s_waitcnt lgkmcnt(0)
	ds_read_b128 v[0:3], v18 offset:8192
	v_or_b32_e32 v18, s24, v118
	s_waitcnt lgkmcnt(0)
	global_store_dwordx4 v[22:23], v[0:3], off
	ds_read_b128 v[0:3], v19 offset:8192
	v_ashrrev_i32_e32 v19, 31, v18
	v_lshlrev_b64 v[18:19], 11, v[18:19]
	v_lshl_add_u64 v[18:19], v[8:9], 0, v[18:19]
	s_waitcnt lgkmcnt(0)
	global_store_dwordx4 v[18:19], v[0:3], off
	ds_read_b128 v[0:3], v20 offset:8192
	v_or_b32_e32 v18, s24, v119
	v_ashrrev_i32_e32 v19, 31, v18
	v_lshlrev_b64 v[18:19], 11, v[18:19]
	v_lshl_add_u64 v[18:19], v[8:9], 0, v[18:19]
	s_waitcnt lgkmcnt(0)
	global_store_dwordx4 v[18:19], v[0:3], off
	ds_read_b128 v[0:3], v4 offset:8192
	v_or_b32_e32 v4, s24, v120
	v_ashrrev_i32_e32 v5, 31, v4
	v_lshlrev_b64 v[4:5], 11, v[4:5]
	v_lshl_add_u64 v[4:5], v[8:9], 0, v[4:5]
	s_waitcnt lgkmcnt(0)
	global_store_dwordx4 v[4:5], v[0:3], off
	s_waitcnt lgkmcnt(0)
	s_branch .LBB0_486

.LBB0_546:
	s_or_b64 exec, exec, s[0:1]
	s_and_saveexec_b64 s[0:1], s[44:45]
	s_cbranch_execz .LBB0_485
	s_or_b32 s4, s24, 31
	s_cmp_ge_i32 s4, s26
	s_cselect_b64 s[6:7], -1, 0
	s_cmp_lt_i32 s4, s27
	s_cselect_b64 s[16:17], -1, 0
	s_and_b64 s[6:7], s[6:7], s[16:17]
	v_mov_b32_e32 v0, 0
	s_andn2_b64 vcc, exec, s[6:7]
	v_mov_b32_e32 v1, 0
	v_mov_b32_e32 v2, 0
	v_mov_b32_e32 v3, 0
	s_cbranch_vccnz .LBB0_484
	v_mad_i64_i32 v[0:1], s[4:5], s4, v208, v[6:7]
	global_load_dwordx4 v[0:3], v[0:1], off
	s_branch .LBB0_484
